# phase 11a hand rewrite (compaction first, copies after gather issue) + phase 11b gather addresses as saddr+32-bit offsets (memory op order and waits unchanged)
# speedup vs baseline: 1.0071x; 1.0062x over previous
; DI void phase11a(const Params& P, char* smem_all) {
;     ...
;     const int E0 = nE0, E1 = nE1; const float G0 = nG0, G1 = nG1, sx = nsx;
;     uint4 xr[4];
; #pragma unroll
;     for (int c = 0; c < 4; ++c) xr[c] = nx[c];
;     bool pf = false;
;     const int tn = t + nw < NTOK ? t + nw : t;
;     if (j == 0) { E2[(long)t * 128 + (lane & 7) * 16 + (lane >> 3)] = E0; E2[(long)t * 128 + (lane & 7) * 16 + 8 + (lane >> 3)] = E1; }
;     const bool in0 = (E0 >> 11) == j, in1 = (E1 >> 11) == j;
;     const unsigned long long m0 = __ballot(in0), m1 = __ballot(in1);
;     const int c0 = __popcll(m0), cnt = c0 + __popcll(m1);
;     const int r0 = __builtin_amdgcn_mbcnt_hi((unsigned)(m0 >> 32), __builtin_amdgcn_mbcnt_lo((unsigned)m0, 0u));
;     const int r1 = c0 + __builtin_amdgcn_mbcnt_hi((unsigned)(m1 >> 32), __builtin_amdgcn_mbcnt_lo((unsigned)m1, 0u));
;     if (in0) lst[r0] = make_uint2((unsigned)E0 | ((unsigned)lane << 14), __float_as_uint(G0));
;     if (in1) lst[r1] = make_uint2((unsigned)E1 | ((unsigned)(64 + lane) << 14), __float_as_uint(G1));
.Lp11a_tok:
	s_waitcnt vmcnt(0) lgkmcnt(0)
	v_lshrrev_b32_e32 v160, 11, v10
	v_lshrrev_b32_e32 v161, 11, v11
	v_cmp_eq_u32_e64 s[44:45], s5, v160
	v_cmp_eq_u32_e64 s[46:47], s5, v161
	v_lshl_or_b32 v162, v10, 10, v208
	v_mov_b32_e32 v163, v12
	v_lshl_or_b32 v164, v11, 10, v166
	v_mov_b32_e32 v165, v13
	s_bcnt1_i32_b64 s10, s[44:45]
	s_bcnt1_i32_b64 s11, s[46:47]
	s_add_i32 s11, s11, s10
	v_mbcnt_lo_u32_b32 v160, s44, 0
	v_mbcnt_hi_u32_b32 v160, s45, v160
	v_mbcnt_lo_u32_b32 v161, s46, 0
	v_mbcnt_hi_u32_b32 v161, s47, v161
	v_add_u32_e32 v161, s10, v161
	v_lshl_add_u32 v160, v160, 3, v4
	v_lshl_add_u32 v161, v161, 3, v4
	v_cndmask_b32_e64 v160, v5, v160, s[44:45]
	v_cndmask_b32_e64 v161, v5, v161, s[46:47]
	ds_write_b64 v160, v[162:163]
	ds_write_b64 v161, v[164:165]
	s_mov_b32 s14, s15
	s_add_i32 s7, s6, s4
	s_cmp_lt_i32 s7, s22
	s_cselect_b32 s7, s7, s6
	s_lshl_b32 s0, s6, 9
	s_add_u32 s36, s24, s0
	s_addc_u32 s37, s25, 0
	s_cmp_eq_u32 s23, 0
	s_cbranch_scc1 .Lp11a_nopend
	s_and_saveexec_b64 s[92:93], s[72:73]
	global_store_dword v192, v193, s[74:75]
	s_mov_b64 exec, s[92:93]
	s_mov_b32 s23, 0
.Lp11a_nopend:
	s_cmp_lg_u32 s5, 0
	s_cbranch_scc1 .Lp11a_noe2
	s_add_u32 s20, s34, s0
	s_addc_u32 s21, s35, 0
	global_store_dword v158, v10, s[20:21]
	global_store_dword v159, v11, s[20:21]
.Lp11a_noe2:
	s_cmp_eq_u32 s11, 0
	s_cbranch_scc1 .Lp11a_empty
	s_add_i32 s18, s11, -1
	s_mov_b32 s12, 0
	s_waitcnt lgkmcnt(0)

; DI void phase11a(const Params& P, char* smem_all) {
;     ...
;       if (!pf) {
;         pf = true;
;         nE0 = Eidx[(long)tn * 128 + lane]; nE1 = Eidx[(long)tn * 128 + 64 + lane];
;         nG0 = G[(long)tn * 128 + lane]; nG1 = G[(long)tn * 128 + 64 + lane];
; #pragma unroll
;         for (int c = 0; c < 4; ++c) nx[c] = *reinterpret_cast<const uint4*>(xq + (long)tn * 1024 + (c * 16 + l16) * 16);
;         nsx = sxp[tn];
.Lp11a_issued:
	v_lshrrev_b32_e32 v175, 8, v154
	v_and_b32_e32 v175, 0xfffc, v175
	global_load_dword v156, v175, s[32:33]
	global_load_dword v153, v175, s[28:29]
	s_cmp_lg_u32 s12, 0
	s_cbranch_scc1 .Lp11a_later
	v_mov_b64_e32 v[16:17], v[32:33]
	v_mov_b64_e32 v[18:19], v[34:35]
	v_mov_b64_e32 v[20:21], v[36:37]
	v_mov_b64_e32 v[22:23], v[38:39]
	v_mov_b64_e32 v[24:25], v[40:41]
	v_mov_b64_e32 v[26:27], v[42:43]
	v_mov_b64_e32 v[28:29], v[44:45]
	v_mov_b64_e32 v[30:31], v[46:47]
	s_lshl_b32 s0, s7, 9
	s_add_u32 s8, s38, s0
	s_addc_u32 s9, s39, 0
	global_load_dword v10, v0, s[8:9]
	global_load_dword v11, v0, s[8:9] offset:256
	s_add_u32 s8, s42, s0
	s_addc_u32 s9, s43, 0
	global_load_dword v12, v0, s[8:9]
	global_load_dword v13, v0, s[8:9] offset:256
	s_lshl_b32 s0, s7, 10
	s_add_u32 s8, s62, s0
	s_addc_u32 s9, s63, 0
	global_load_dwordx4 v[32:35], v1, s[8:9]
	global_load_dwordx4 v[36:39], v1, s[8:9] offset:256
	global_load_dwordx4 v[40:43], v1, s[8:9] offset:512
	global_load_dwordx4 v[44:47], v1, s[8:9] offset:768
	s_lshl_b32 s0, s7, 2
	s_add_u32 s8, s30, s0
	s_addc_u32 s9, s31, 0
	s_load_dword s15, s[8:9], 0x0
	s_cmp_eq_u32 s13, 4
	s_cbranch_scc1 .Lp11a_d4
	s_cmp_eq_u32 s13, 5
	s_cbranch_scc1 .Lp11a_d5
	s_cmp_eq_u32 s13, 3
	s_cbranch_scc1 .Lp11a_d3
	s_cmp_eq_u32 s13, 6
	s_cbranch_scc1 .Lp11a_d6
	s_cmp_eq_u32 s13, 2
	s_cbranch_scc1 .Lp11a_d2

; DI void phase11a(const Params& P, char* smem_all) {
;     ...
;     if (!pf) {
;       nE0 = Eidx[(long)tn * 128 + lane]; nE1 = Eidx[(long)tn * 128 + 64 + lane];
;       nG0 = G[(long)tn * 128 + lane]; nG1 = G[(long)tn * 128 + 64 + lane];
; #pragma unroll
;       for (int c = 0; c < 4; ++c) nx[c] = *reinterpret_cast<const uint4*>(xq + (long)tn * 1024 + (c * 16 + l16) * 16);
;       nsx = sxp[tn];
;     }
.Lp11a_empty:
	v_mov_b64_e32 v[16:17], v[32:33]
	v_mov_b64_e32 v[18:19], v[34:35]
	v_mov_b64_e32 v[20:21], v[36:37]
	v_mov_b64_e32 v[22:23], v[38:39]
	v_mov_b64_e32 v[24:25], v[40:41]
	v_mov_b64_e32 v[26:27], v[42:43]
	v_mov_b64_e32 v[28:29], v[44:45]
	v_mov_b64_e32 v[30:31], v[46:47]
	s_lshl_b32 s0, s7, 9
	s_add_u32 s8, s38, s0
	s_addc_u32 s9, s39, 0
	global_load_dword v10, v0, s[8:9]
	global_load_dword v11, v0, s[8:9] offset:256
	s_add_u32 s8, s42, s0
	s_addc_u32 s9, s43, 0
	global_load_dword v12, v0, s[8:9]
	global_load_dword v13, v0, s[8:9] offset:256
	s_lshl_b32 s0, s7, 10
	s_add_u32 s8, s62, s0
	s_addc_u32 s9, s63, 0
	global_load_dwordx4 v[32:35], v1, s[8:9]
	global_load_dwordx4 v[36:39], v1, s[8:9] offset:256
	global_load_dwordx4 v[40:43], v1, s[8:9] offset:512
	global_load_dwordx4 v[44:47], v1, s[8:9] offset:768
	s_lshl_b32 s0, s7, 2
	s_add_u32 s8, s30, s0
	s_addc_u32 s9, s31, 0
	s_load_dword s15, s[8:9], 0x0
	s_waitcnt vmcnt(0)
	s_branch .Lp11a_next

; DI void phase11b(const Params& P, char* smem_all) {
;     ...
;   const int j = RBLK & 7, lane = RTID & 63, wv = RTID >> 6, wslot = (RBLK >> 3) * 8 + wv, nw = (RGRID >> 3) * 8;
;   float* red = (float*)(smem_all + wv * 4096);
;   const char* vbase = Vq + (long)j * 16384 * 128 + (lane & 7) * 16;
;   const int g8 = lane >> 3;
;   int4 en[4]; float4 wn[4];
;   auto load_list = [&](int t) {
; #pragma unroll
;     for (int k = 0; k < 4; ++k) {
;       en[k] = *reinterpret_cast<const int4*>(E2 + (long)t * 128 + g8 * 16 + 4 * k);
;       wn[k] = *reinterpret_cast<const float4*>(W2 + (long)t * 128 + g8 * 16 + 4 * k);
;     }
;   };
;   auto gather = [&](uint4 (&v)[16], float (&w)[16]) {
; #pragma unroll
;     for (int k = 0; k < 4; ++k) {
;       v[4 * k] = *reinterpret_cast<const uint4*>(vbase + (long)en[k].x * 128); v[4 * k + 1] = *reinterpret_cast<const uint4*>(vbase + (long)en[k].y * 128);
;       v[4 * k + 2] = *reinterpret_cast<const uint4*>(vbase + (long)en[k].z * 128); v[4 * k + 3] = *reinterpret_cast<const uint4*>(vbase + (long)en[k].w * 128);
;       w[4 * k] = wn[k].x; w[4 * k + 1] = wn[k].y; w[4 * k + 2] = wn[k].z; w[4 * k + 3] = wn[k].w;
;     }
;   };
;   auto reduce_store = [&](const uint4 (&v)[16], const float (&w)[16], int t) {
;     typedef float f2 __attribute__((ext_vector_type(2)));
;     f2 acc[8]; float wl = 0.f;
; #pragma unroll
;     for (int k = 0; k < 8; ++k) acc[k] = f2{0.f, 0.f};
; #pragma unroll
;     for (int r = 0; r < 16; ++r) {
;       wl += w[r];
;       const f2 w2 = f2{w[r], w[r]};
;       const unsigned vw[4] = {v[r].x, v[r].y, v[r].z, v[r].w};
; #pragma unroll
;       for (int k = 0; k < 4; ++k) {
;         acc[2 * k + 0] = __builtin_elementwise_fma(w2, f2{(float)(vw[k] & 0xffu), (float)((vw[k] >> 8) & 0xffu)}, acc[2 * k + 0]);
;         acc[2 * k + 1] = __builtin_elementwise_fma(w2, f2{(float)((vw[k] >> 16) & 0xffu), (float)(vw[k] >> 24)}, acc[2 * k + 1]);
;       }
;     }
;     const float rsum = dpp_row_sum_f(wl);
;     const float wsum = (__int_as_float(__builtin_amdgcn_readlane(__float_as_int(rsum), 0)) + __int_as_float(__builtin_amdgcn_readlane(__float_as_int(rsum), 16)) +
;                         __int_as_float(__builtin_amdgcn_readlane(__float_as_int(rsum), 32)) + __int_as_float(__builtin_amdgcn_readlane(__float_as_int(rsum), 48))) * 0.125f;
; #pragma unroll
.LBB0_1577:
	s_or_b64 exec, exec, s[0:1]
	s_waitcnt lgkmcnt(0)
	s_barrier
	s_and_saveexec_b64 s[6:7], s[2:3]
	s_cbranch_execz .LBB0_1582
	s_add_u32 s0, s78, 0x1c200000
	s_addc_u32 s1, s79, 0
	v_mov_b32_e32 v37, 0
	v_lshrrev_b32_e32 v90, 3, v208
	v_lshlrev_b64 v[40:41], 9, v[212:213]
	v_lshlrev_b32_e32 v38, 6, v90
	v_mov_b32_e32 v39, v37
	v_lshl_add_u64 v[0:1], s[0:1], 0, v[40:41]
	v_lshl_add_u64 v[0:1], v[0:1], 0, v[38:39]
	global_load_dwordx4 v[4:7], v[0:1], off offset:48
	global_load_dwordx4 v[8:11], v[0:1], off offset:32
	global_load_dwordx4 v[16:19], v[0:1], off offset:16
	global_load_dwordx4 v[42:45], v[0:1], off
	v_add_u32_e32 v0, s4, v212
	s_mov_b32 s14, 0x8000
	v_cmp_gt_i32_e32 vcc, s14, v0
	s_lshl_b32 s8, s5, 21
	s_add_u32 s8, s78, s8
	v_cndmask_b32_e32 v0, v212, v0, vcc
	v_ashrrev_i32_e32 v1, 31, v0
	v_lshlrev_b64 v[0:1], 9, v[0:1]
	v_and_b32_e32 v36, 0x70, v209
	s_addc_u32 s9, s79, 0
	s_add_u32 s26, s8, 0x1000000
	s_addc_u32 s27, s9, 0
	v_and_b32_e32 v227, 0x70, v209
	v_lshl_add_u64 v[12:13], s[24:25], 0, v[0:1]
	v_lshl_add_u64 v[0:1], s[0:1], 0, v[0:1]
	s_mov_b64 s[2:3], 0x1000000
	v_lshl_add_u64 v[2:3], s[8:9], 0, v[36:37]
	v_lshl_add_u64 v[20:21], v[12:13], 0, v[38:39]
	v_lshl_add_u64 v[22:23], v[0:1], 0, v[38:39]
	v_lshl_add_u64 v[214:215], v[2:3], 0, s[2:3]
	global_load_dwordx4 v[0:3], v[20:21], off offset:48
	global_load_dwordx4 v[12:15], v[20:21], off offset:32
	global_load_dwordx4 v[24:27], v[20:21], off offset:16
	global_load_dwordx4 v[60:63], v[20:21], off
	global_load_dwordx4 v[96:99], v[22:23], off offset:48
	global_load_dwordx4 v[108:111], v[22:23], off offset:32
	global_load_dwordx4 v[120:123], v[22:23], off offset:16
	global_load_dwordx4 v[128:131], v[22:23], off
	v_lshl_add_u64 v[40:41], s[24:25], 0, v[40:41]
	v_lshl_add_u64 v[40:41], v[40:41], 0, v[38:39]
	s_lshl_b32 s2, s4, 1
	s_lshl_b32 s3, s5, 8
	v_lshl_add_u64 v[216:217], s[0:1], 0, v[38:39]
	v_lshl_add_u64 v[218:219], s[24:25], 0, v[38:39]
	v_lshl_add_u32 v38, v172, 12, 0
	s_add_u32 s0, s78, s3
	s_addc_u32 s1, s79, 0
	v_lshl_add_u32 v224, v208, 3, v38
	s_mul_i32 s5, s4, 3
	s_mov_b64 s[10:11], 0
	v_mov_b32_e32 v225, v212
	s_waitcnt vmcnt(11)
	v_ashrrev_i32_e32 v21, 31, v7
	v_mov_b32_e32 v20, v7
	v_ashrrev_i32_e32 v23, 31, v5
	v_mov_b32_e32 v22, v5
	v_ashrrev_i32_e32 v5, 31, v4
	s_waitcnt vmcnt(10)
	v_ashrrev_i32_e32 v29, 31, v11
	v_mov_b32_e32 v28, v11
	v_ashrrev_i32_e32 v31, 31, v9
	v_mov_b32_e32 v30, v9
	v_ashrrev_i32_e32 v9, 31, v8
	s_waitcnt vmcnt(9)
	v_ashrrev_i32_e32 v33, 31, v19
	v_mov_b32_e32 v32, v19
	v_ashrrev_i32_e32 v47, 31, v17
	v_mov_b32_e32 v46, v17
	v_ashrrev_i32_e32 v7, 31, v6
	v_ashrrev_i32_e32 v11, 31, v10
	v_ashrrev_i32_e32 v19, 31, v18
	v_ashrrev_i32_e32 v17, 31, v16
	v_lshlrev_b64 v[20:21], 7, v[20:21]
	v_lshlrev_b64 v[4:5], 7, v[4:5]
	v_lshlrev_b64 v[28:29], 7, v[28:29]
	v_lshlrev_b64 v[8:9], 7, v[8:9]
	v_lshlrev_b64 v[32:33], 7, v[32:33]
	v_lshlrev_b64 v[46:47], 7, v[46:47]
	v_lshlrev_b64 v[6:7], 7, v[6:7]
	v_lshlrev_b64 v[22:23], 7, v[22:23]
	v_lshlrev_b64 v[10:11], 7, v[10:11]
	v_lshlrev_b64 v[30:31], 7, v[30:31]
	v_lshlrev_b64 v[18:19], 7, v[18:19]
	v_lshlrev_b64 v[48:49], 7, v[16:17]
	v_lshl_add_u64 v[50:51], v[214:215], 0, v[20:21]
	v_lshl_add_u64 v[76:77], v[214:215], 0, v[4:5]
	v_lshl_add_u64 v[78:79], v[214:215], 0, v[28:29]
	v_lshl_add_u64 v[84:85], v[214:215], 0, v[8:9]
	v_lshl_add_u64 v[86:87], v[214:215], 0, v[32:33]
	v_lshl_add_u64 v[46:47], v[214:215], 0, v[46:47]
	v_lshl_add_u64 v[72:73], v[214:215], 0, v[6:7]
	v_lshl_add_u64 v[74:75], v[214:215], 0, v[22:23]
	v_lshl_add_u64 v[80:81], v[214:215], 0, v[10:11]
	v_lshl_add_u64 v[82:83], v[214:215], 0, v[30:31]
	v_lshl_add_u64 v[88:89], v[214:215], 0, v[18:19]
	global_load_dwordx4 v[4:7], v[50:51], off
	global_load_dwordx4 v[8:11], v[72:73], off
	global_load_dwordx4 v[16:19], v[74:75], off
	global_load_dwordx4 v[20:23], v[76:77], off
	global_load_dwordx4 v[28:31], v[78:79], off
	global_load_dwordx4 v[32:35], v[80:81], off
	global_load_dwordx4 v[52:55], v[82:83], off
	global_load_dwordx4 v[56:59], v[84:85], off
	global_load_dwordx4 v[64:67], v[86:87], off
	global_load_dwordx4 v[68:71], v[88:89], off
	v_lshl_add_u64 v[48:49], v[214:215], 0, v[48:49]
	global_load_dwordx4 v[76:79], v[46:47], off
	global_load_dwordx4 v[84:87], v[48:49], off
	s_waitcnt vmcnt(20)
	v_ashrrev_i32_e32 v47, 31, v45
	v_mov_b32_e32 v46, v45
	v_ashrrev_i32_e32 v45, 31, v44
	v_lshlrev_b64 v[44:45], 7, v[44:45]
	v_lshlrev_b64 v[46:47], 7, v[46:47]
	v_lshl_add_u64 v[46:47], v[214:215], 0, v[46:47]
	v_lshl_add_u64 v[44:45], v[214:215], 0, v[44:45]
	global_load_dwordx4 v[100:103], v[46:47], off
	global_load_dwordx4 v[112:115], v[44:45], off
	v_ashrrev_i32_e32 v45, 31, v43
	v_mov_b32_e32 v44, v43
	v_ashrrev_i32_e32 v43, 31, v42
	v_lshlrev_b64 v[44:45], 7, v[44:45]
	v_lshlrev_b64 v[42:43], 7, v[42:43]
	v_lshl_add_u64 v[44:45], v[214:215], 0, v[44:45]
	v_lshl_add_u64 v[42:43], v[214:215], 0, v[42:43]
	global_load_dwordx4 v[132:135], v[44:45], off
	global_load_dwordx4 v[144:147], v[42:43], off
	global_load_dwordx4 v[168:171], v[40:41], off offset:48
	global_load_dwordx4 v[196:199], v[40:41], off offset:32
	global_load_dwordx4 v[200:203], v[40:41], off offset:16
	global_load_dwordx4 v[204:207], v[40:41], off
	v_lshl_add_u32 v40, v36, 2, v38
	v_lshlrev_b32_e32 v36, 2, v208
	v_lshl_add_u64 v[38:39], s[0:1], 0, v[36:37]
	s_mov_b64 s[0:1], 0xa000000
	v_lshl_add_u64 v[220:221], v[38:39], 0, s[0:1]
	v_lshlrev_b64 v[38:39], 11, v[212:213]
	v_or3_b32 v38, v38, s3, v36
	v_lshlrev_b32_e32 v41, 9, v90
	v_lshl_add_u64 v[36:37], s[78:79], 0, v[38:39]
	s_ashr_i32 s3, s2, 31
	v_lshl_add_u64 v[222:223], v[36:37], 0, s[0:1]
	s_lshl_b64 s[8:9], s[2:3], 11
	s_movk_i32 s3, 0x7fff
	v_add_u32_e32 v213, v40, v41
	s_branch .LBB0_1580

; DI void phase11b(const Params& P, char* smem_all) {
;     ...
;   auto gather = [&](uint4 (&v)[16], float (&w)[16]) {
; #pragma unroll
;     for (int k = 0; k < 4; ++k) {
;       v[4 * k] = *reinterpret_cast<const uint4*>(vbase + (long)en[k].x * 128); v[4 * k + 1] = *reinterpret_cast<const uint4*>(vbase + (long)en[k].y * 128);
;       v[4 * k + 2] = *reinterpret_cast<const uint4*>(vbase + (long)en[k].z * 128); v[4 * k + 3] = *reinterpret_cast<const uint4*>(vbase + (long)en[k].w * 128);
;       w[4 * k] = wn[k].x; w[4 * k + 1] = wn[k].y; w[4 * k + 2] = wn[k].z; w[4 * k + 3] = wn[k].w;
;     }
;   };
;   auto reduce_store = [&](const uint4 (&v)[16], const float (&w)[16], int t) {
;     typedef float f2 __attribute__((ext_vector_type(2)));
;     f2 acc[8]; float wl = 0.f;
; #pragma unroll
;     for (int k = 0; k < 8; ++k) acc[k] = f2{0.f, 0.f};
; #pragma unroll
;     for (int r = 0; r < 16; ++r) {
;       wl += w[r];
;       const f2 w2 = f2{w[r], w[r]};
;       const unsigned vw[4] = {v[r].x, v[r].y, v[r].z, v[r].w};
; #pragma unroll
;       for (int k = 0; k < 4; ++k) {
;         acc[2 * k + 0] = __builtin_elementwise_fma(w2, f2{(float)(vw[k] & 0xffu), (float)((vw[k] >> 8) & 0xffu)}, acc[2 * k + 0]);
;         acc[2 * k + 1] = __builtin_elementwise_fma(w2, f2{(float)((vw[k] >> 16) & 0xffu), (float)(vw[k] >> 24)}, acc[2 * k + 1]);
;       }
.LBB0_1580:
	s_waitcnt vmcnt(20)
	v_lshl_add_u32 v246, v128, 7, v227
	v_lshl_add_u32 v247, v129, 7, v227
	v_lshl_add_u32 v248, v130, 7, v227
	v_lshl_add_u32 v249, v131, 7, v227
	v_lshl_add_u32 v250, v120, 7, v227
	v_lshl_add_u32 v251, v121, 7, v227
	global_load_dwordx4 v[176:179], v246, s[26:27]
	global_load_dwordx4 v[172:175], v247, s[26:27]
	global_load_dwordx4 v[164:167], v248, s[26:27]
	global_load_dwordx4 v[160:163], v249, s[26:27]
	global_load_dwordx4 v[156:159], v250, s[26:27]
	global_load_dwordx4 v[152:155], v251, s[26:27]
	v_lshl_add_u32 v246, v122, 7, v227
	v_lshl_add_u32 v247, v123, 7, v227
	v_lshl_add_u32 v248, v108, 7, v227
	v_lshl_add_u32 v249, v109, 7, v227
	v_lshl_add_u32 v250, v110, 7, v227
	v_lshl_add_u32 v251, v111, 7, v227
	global_load_dwordx4 v[148:151], v246, s[26:27]
	global_load_dwordx4 v[140:143], v247, s[26:27]
	global_load_dwordx4 v[136:139], v248, s[26:27]
	global_load_dwordx4 v[124:127], v249, s[26:27]
	global_load_dwordx4 v[116:119], v250, s[26:27]
	global_load_dwordx4 v[104:107], v251, s[26:27]
	v_lshl_add_u32 v246, v96, 7, v227
	v_lshl_add_u32 v247, v97, 7, v227
	global_load_dwordx4 v[92:95], v246, s[26:27]
	global_load_dwordx4 v[88:91], v247, s[26:27]
	v_lshl_add_u32 v252, v98, 7, v227
	v_lshl_add_u32 v253, v99, 7, v227
	s_waitcnt vmcnt(18)
	v_cvt_f32_ubyte1_e32 v99, v144
	v_cvt_f32_ubyte0_e32 v98, v144
	s_waitcnt vmcnt(14)
	v_pk_fma_f32 v[98:99], v[204:205], v[98:99], 0 op_sel_hi:[0,1,0]
	v_cvt_f32_ubyte3_e32 v109, v144
	v_cvt_f32_ubyte2_e32 v108, v144
	v_cvt_f32_ubyte1_e32 v111, v145
	v_cvt_f32_ubyte0_e32 v110, v145
	v_cvt_f32_ubyte3_e32 v121, v145
	v_cvt_f32_ubyte2_e32 v120, v145
	v_cvt_f32_ubyte1_e32 v123, v146
	v_cvt_f32_ubyte0_e32 v122, v146
	v_cvt_f32_ubyte3_e32 v129, v146
	v_cvt_f32_ubyte2_e32 v128, v146
	v_cvt_f32_ubyte1_e32 v131, v147
	v_cvt_f32_ubyte0_e32 v130, v147
	v_cvt_f32_ubyte3_e32 v145, v147
	v_cvt_f32_ubyte2_e32 v144, v147
	v_cvt_f32_ubyte1_e32 v147, v132
	v_cvt_f32_ubyte0_e32 v146, v132
	v_pk_fma_f32 v[108:109], v[204:205], v[108:109], 0 op_sel_hi:[0,1,0]
	v_pk_fma_f32 v[98:99], v[204:205], v[146:147], v[98:99] op_sel:[1,0,0]
	v_cvt_f32_ubyte3_e32 v147, v132
	v_cvt_f32_ubyte2_e32 v146, v132
	v_pk_fma_f32 v[110:111], v[204:205], v[110:111], 0 op_sel_hi:[0,1,0]
	v_pk_fma_f32 v[108:109], v[204:205], v[146:147], v[108:109] op_sel:[1,0,0]
	v_cvt_f32_ubyte1_e32 v147, v133
	v_cvt_f32_ubyte0_e32 v146, v133
	v_pk_fma_f32 v[122:123], v[204:205], v[122:123], 0 op_sel_hi:[0,1,0]
	v_pk_fma_f32 v[110:111], v[204:205], v[146:147], v[110:111] op_sel:[1,0,0]
	v_cvt_f32_ubyte3_e32 v147, v133
	v_cvt_f32_ubyte2_e32 v146, v133
	v_cvt_f32_ubyte1_e32 v133, v134
	v_cvt_f32_ubyte0_e32 v132, v134
	v_pk_fma_f32 v[128:129], v[204:205], v[128:129], 0 op_sel_hi:[0,1,0]
	v_pk_fma_f32 v[122:123], v[204:205], v[132:133], v[122:123] op_sel:[1,0,0]
	v_cvt_f32_ubyte3_e32 v133, v134
	v_cvt_f32_ubyte2_e32 v132, v134
	v_pk_fma_f32 v[130:131], v[204:205], v[130:131], 0 op_sel_hi:[0,1,0]
	v_pk_fma_f32 v[128:129], v[204:205], v[132:133], v[128:129] op_sel:[1,0,0]
	v_cvt_f32_ubyte1_e32 v133, v135
	v_cvt_f32_ubyte0_e32 v132, v135
	v_pk_fma_f32 v[130:131], v[204:205], v[132:133], v[130:131] op_sel:[1,0,0]
	v_cvt_f32_ubyte3_e32 v133, v135
	v_cvt_f32_ubyte2_e32 v132, v135
	v_cvt_f32_ubyte1_e32 v135, v112
	v_cvt_f32_ubyte0_e32 v134, v112
	v_pk_fma_f32 v[98:99], v[206:207], v[134:135], v[98:99] op_sel_hi:[0,1,1]
	v_cvt_f32_ubyte3_e32 v135, v112
	v_cvt_f32_ubyte2_e32 v134, v112
	v_pk_fma_f32 v[120:121], v[204:205], v[120:121], 0 op_sel_hi:[0,1,0]
	v_pk_fma_f32 v[108:109], v[206:207], v[134:135], v[108:109] op_sel_hi:[0,1,1]
	v_cvt_f32_ubyte1_e32 v135, v113
	v_cvt_f32_ubyte0_e32 v134, v113
	v_pk_fma_f32 v[120:121], v[204:205], v[146:147], v[120:121] op_sel:[1,0,0]
	v_pk_fma_f32 v[110:111], v[206:207], v[134:135], v[110:111] op_sel_hi:[0,1,1]
	v_cvt_f32_ubyte3_e32 v135, v113
	v_cvt_f32_ubyte2_e32 v134, v113
	v_pk_fma_f32 v[112:113], v[206:207], v[134:135], v[120:121] op_sel_hi:[0,1,1]
	v_cvt_f32_ubyte1_e32 v121, v114
	v_cvt_f32_ubyte0_e32 v120, v114
	v_pk_fma_f32 v[120:121], v[206:207], v[120:121], v[122:123] op_sel_hi:[0,1,1]
	v_cvt_f32_ubyte3_e32 v123, v114
	v_cvt_f32_ubyte2_e32 v122, v114
	v_pk_fma_f32 v[144:145], v[204:205], v[144:145], 0 op_sel_hi:[0,1,0]
	v_pk_fma_f32 v[122:123], v[206:207], v[122:123], v[128:129] op_sel_hi:[0,1,1]
	v_cvt_f32_ubyte1_e32 v129, v115
	v_cvt_f32_ubyte0_e32 v128, v115
	v_pk_fma_f32 v[132:133], v[204:205], v[132:133], v[144:145] op_sel:[1,0,0]
	v_pk_fma_f32 v[128:129], v[206:207], v[128:129], v[130:131] op_sel_hi:[0,1,1]
	v_cvt_f32_ubyte3_e32 v131, v115
	v_cvt_f32_ubyte2_e32 v130, v115
	v_pk_fma_f32 v[114:115], v[206:207], v[130:131], v[132:133] op_sel_hi:[0,1,1]
	v_cvt_f32_ubyte1_e32 v131, v100
	v_cvt_f32_ubyte0_e32 v130, v100
	v_pk_fma_f32 v[98:99], v[206:207], v[130:131], v[98:99] op_sel:[1,0,0]
	v_cvt_f32_ubyte3_e32 v131, v100
	v_cvt_f32_ubyte2_e32 v130, v100
	v_pk_fma_f32 v[108:109], v[206:207], v[130:131], v[108:109] op_sel:[1,0,0]
	v_cvt_f32_ubyte1_e32 v131, v101
	v_cvt_f32_ubyte0_e32 v130, v101
	v_pk_fma_f32 v[110:111], v[206:207], v[130:131], v[110:111] op_sel:[1,0,0]
	v_cvt_f32_ubyte3_e32 v131, v101
	v_cvt_f32_ubyte2_e32 v130, v101
	v_pk_fma_f32 v[100:101], v[206:207], v[130:131], v[112:113] op_sel:[1,0,0]
	v_cvt_f32_ubyte1_e32 v113, v102
	v_cvt_f32_ubyte0_e32 v112, v102
	v_pk_fma_f32 v[112:113], v[206:207], v[112:113], v[120:121] op_sel:[1,0,0]
	v_cvt_f32_ubyte3_e32 v121, v102
	v_cvt_f32_ubyte2_e32 v120, v102
	v_pk_fma_f32 v[120:121], v[206:207], v[120:121], v[122:123] op_sel:[1,0,0]
	v_cvt_f32_ubyte1_e32 v123, v103
	v_cvt_f32_ubyte0_e32 v122, v103
	v_pk_fma_f32 v[122:123], v[206:207], v[122:123], v[128:129] op_sel:[1,0,0]
; DI void phase11b(const Params& P, char* smem_all) {
;     ...
;   auto reduce_store = [&](const uint4 (&v)[16], const float (&w)[16], int t) {
;     typedef float f2 __attribute__((ext_vector_type(2)));
;     f2 acc[8]; float wl = 0.f;
; #pragma unroll
;     for (int k = 0; k < 8; ++k) acc[k] = f2{0.f, 0.f};
; #pragma unroll
;     for (int r = 0; r < 16; ++r) {
;       wl += w[r];
;       const f2 w2 = f2{w[r], w[r]};
;       const unsigned vw[4] = {v[r].x, v[r].y, v[r].z, v[r].w};
; #pragma unroll
;       for (int k = 0; k < 4; ++k) {
;         acc[2 * k + 0] = __builtin_elementwise_fma(w2, f2{(float)(vw[k] & 0xffu), (float)((vw[k] >> 8) & 0xffu)}, acc[2 * k + 0]);
;         acc[2 * k + 1] = __builtin_elementwise_fma(w2, f2{(float)((vw[k] >> 16) & 0xffu), (float)(vw[k] >> 24)}, acc[2 * k + 1]);
;       }
;     }
	v_cvt_f32_ubyte3_e32 v129, v103
	v_cvt_f32_ubyte2_e32 v128, v103
	v_pk_fma_f32 v[102:103], v[206:207], v[128:129], v[114:115] op_sel:[1,0,0]
	v_cvt_f32_ubyte1_e32 v115, v84
	v_cvt_f32_ubyte0_e32 v114, v84
	v_pk_fma_f32 v[98:99], v[200:201], v[114:115], v[98:99] op_sel_hi:[0,1,1]
	v_cvt_f32_ubyte3_e32 v115, v84
	v_cvt_f32_ubyte2_e32 v114, v84
	v_pk_fma_f32 v[108:109], v[200:201], v[114:115], v[108:109] op_sel_hi:[0,1,1]
	v_cvt_f32_ubyte1_e32 v115, v85
	v_cvt_f32_ubyte0_e32 v114, v85
	v_pk_fma_f32 v[110:111], v[200:201], v[114:115], v[110:111] op_sel_hi:[0,1,1]
	v_cvt_f32_ubyte3_e32 v115, v85
	v_cvt_f32_ubyte2_e32 v114, v85
	v_pk_fma_f32 v[84:85], v[200:201], v[114:115], v[100:101] op_sel_hi:[0,1,1]
	v_cvt_f32_ubyte1_e32 v101, v86
	v_cvt_f32_ubyte0_e32 v100, v86
	v_pk_fma_f32 v[100:101], v[200:201], v[100:101], v[112:113] op_sel_hi:[0,1,1]
	v_cvt_f32_ubyte3_e32 v113, v86
	v_cvt_f32_ubyte2_e32 v112, v86
	v_pk_fma_f32 v[112:113], v[200:201], v[112:113], v[120:121] op_sel_hi:[0,1,1]
	v_cvt_f32_ubyte3_e32 v121, v87
	v_cvt_f32_ubyte2_e32 v120, v87
	v_cvt_f32_ubyte1_e32 v115, v87
	v_cvt_f32_ubyte0_e32 v114, v87
	v_pk_fma_f32 v[86:87], v[200:201], v[120:121], v[102:103] op_sel_hi:[0,1,1]
	v_cvt_f32_ubyte1_e32 v103, v76
	v_cvt_f32_ubyte0_e32 v102, v76
	v_pk_fma_f32 v[98:99], v[200:201], v[102:103], v[98:99] op_sel:[1,0,0]
	v_cvt_f32_ubyte3_e32 v103, v76
	v_cvt_f32_ubyte2_e32 v102, v76
	v_pk_fma_f32 v[102:103], v[200:201], v[102:103], v[108:109] op_sel:[1,0,0]
	v_cvt_f32_ubyte1_e32 v109, v77
	v_cvt_f32_ubyte0_e32 v108, v77
	v_pk_fma_f32 v[108:109], v[200:201], v[108:109], v[110:111] op_sel:[1,0,0]
	v_cvt_f32_ubyte3_e32 v111, v77
	v_cvt_f32_ubyte2_e32 v110, v77
	v_pk_fma_f32 v[76:77], v[200:201], v[110:111], v[84:85] op_sel:[1,0,0]
	v_cvt_f32_ubyte1_e32 v85, v78
	v_cvt_f32_ubyte0_e32 v84, v78
	v_pk_fma_f32 v[84:85], v[200:201], v[84:85], v[100:101] op_sel:[1,0,0]
	v_cvt_f32_ubyte3_e32 v101, v78
	v_cvt_f32_ubyte2_e32 v100, v78
	v_pk_fma_f32 v[100:101], v[200:201], v[100:101], v[112:113] op_sel:[1,0,0]
	v_cvt_f32_ubyte3_e32 v113, v79
	v_cvt_f32_ubyte2_e32 v112, v79
	v_cvt_f32_ubyte1_e32 v111, v79
	v_cvt_f32_ubyte0_e32 v110, v79
	v_pk_fma_f32 v[78:79], v[200:201], v[112:113], v[86:87] op_sel:[1,0,0]
	v_cvt_f32_ubyte1_e32 v87, v68
	v_cvt_f32_ubyte0_e32 v86, v68
	v_pk_fma_f32 v[86:87], v[202:203], v[86:87], v[98:99] op_sel_hi:[0,1,1]
	v_cvt_f32_ubyte3_e32 v99, v68
	v_cvt_f32_ubyte2_e32 v98, v68
	v_pk_fma_f32 v[98:99], v[202:203], v[98:99], v[102:103] op_sel_hi:[0,1,1]
	v_cvt_f32_ubyte1_e32 v103, v69
	v_cvt_f32_ubyte0_e32 v102, v69
	v_pk_fma_f32 v[102:103], v[202:203], v[102:103], v[108:109] op_sel_hi:[0,1,1]
	v_cvt_f32_ubyte3_e32 v109, v69
	v_cvt_f32_ubyte2_e32 v108, v69
	v_pk_fma_f32 v[68:69], v[202:203], v[108:109], v[76:77] op_sel_hi:[0,1,1]
	v_cvt_f32_ubyte1_e32 v77, v70
	v_cvt_f32_ubyte0_e32 v76, v70
	v_pk_fma_f32 v[76:77], v[202:203], v[76:77], v[84:85] op_sel_hi:[0,1,1]
	v_cvt_f32_ubyte3_e32 v85, v70
	v_cvt_f32_ubyte2_e32 v84, v70
	v_cvt_f32_ubyte3_e32 v109, v71
	v_cvt_f32_ubyte2_e32 v108, v71
	v_pk_fma_f32 v[84:85], v[202:203], v[84:85], v[100:101] op_sel_hi:[0,1,1]
	v_cvt_f32_ubyte1_e32 v101, v71
	v_cvt_f32_ubyte0_e32 v100, v71
	v_pk_fma_f32 v[70:71], v[202:203], v[108:109], v[78:79] op_sel_hi:[0,1,1]
	v_cvt_f32_ubyte1_e32 v79, v64
	v_cvt_f32_ubyte0_e32 v78, v64
	v_pk_fma_f32 v[78:79], v[202:203], v[78:79], v[86:87] op_sel:[1,0,0]
	v_cvt_f32_ubyte3_e32 v87, v64
	v_cvt_f32_ubyte2_e32 v86, v64
	v_pk_fma_f32 v[86:87], v[202:203], v[86:87], v[98:99] op_sel:[1,0,0]
	v_cvt_f32_ubyte1_e32 v99, v65
	v_cvt_f32_ubyte0_e32 v98, v65
	v_pk_fma_f32 v[98:99], v[202:203], v[98:99], v[102:103] op_sel:[1,0,0]
	v_cvt_f32_ubyte3_e32 v103, v65
	v_cvt_f32_ubyte2_e32 v102, v65
	v_pk_fma_f32 v[114:115], v[200:201], v[114:115], v[122:123] op_sel_hi:[0,1,1]
	v_pk_fma_f32 v[64:65], v[202:203], v[102:103], v[68:69] op_sel:[1,0,0]
	v_cvt_f32_ubyte1_e32 v69, v66
	v_cvt_f32_ubyte0_e32 v68, v66
	v_pk_fma_f32 v[110:111], v[200:201], v[110:111], v[114:115] op_sel:[1,0,0]
	v_pk_fma_f32 v[68:69], v[202:203], v[68:69], v[76:77] op_sel:[1,0,0]
	v_cvt_f32_ubyte3_e32 v77, v66
	v_cvt_f32_ubyte2_e32 v76, v66
	v_pk_fma_f32 v[100:101], v[202:203], v[100:101], v[110:111] op_sel_hi:[0,1,1]
	v_pk_fma_f32 v[76:77], v[202:203], v[76:77], v[84:85] op_sel:[1,0,0]
	v_cvt_f32_ubyte1_e32 v85, v67
	v_cvt_f32_ubyte0_e32 v84, v67
	v_pk_fma_f32 v[84:85], v[202:203], v[84:85], v[100:101] op_sel:[1,0,0]
	v_cvt_f32_ubyte3_e32 v101, v67
	v_cvt_f32_ubyte2_e32 v100, v67
	v_pk_fma_f32 v[66:67], v[202:203], v[100:101], v[70:71] op_sel:[1,0,0]
	v_cvt_f32_ubyte1_e32 v71, v56
	v_cvt_f32_ubyte0_e32 v70, v56
	v_pk_fma_f32 v[70:71], v[196:197], v[70:71], v[78:79] op_sel_hi:[0,1,1]
	v_cvt_f32_ubyte3_e32 v79, v56
	v_cvt_f32_ubyte2_e32 v78, v56
	v_pk_fma_f32 v[78:79], v[196:197], v[78:79], v[86:87] op_sel_hi:[0,1,1]
	v_cvt_f32_ubyte1_e32 v87, v57
	v_cvt_f32_ubyte0_e32 v86, v57
	v_pk_fma_f32 v[86:87], v[196:197], v[86:87], v[98:99] op_sel_hi:[0,1,1]
	v_cvt_f32_ubyte3_e32 v99, v57
	v_cvt_f32_ubyte2_e32 v98, v57
	v_pk_fma_f32 v[56:57], v[196:197], v[98:99], v[64:65] op_sel_hi:[0,1,1]
	v_cvt_f32_ubyte1_e32 v65, v58
	v_cvt_f32_ubyte0_e32 v64, v58
	v_pk_fma_f32 v[64:65], v[196:197], v[64:65], v[68:69] op_sel_hi:[0,1,1]
	v_cvt_f32_ubyte3_e32 v69, v58
	v_cvt_f32_ubyte2_e32 v68, v58
	v_pk_fma_f32 v[68:69], v[196:197], v[68:69], v[76:77] op_sel_hi:[0,1,1]
	v_cvt_f32_ubyte1_e32 v77, v59
	v_cvt_f32_ubyte0_e32 v76, v59
	v_pk_fma_f32 v[76:77], v[196:197], v[76:77], v[84:85] op_sel_hi:[0,1,1]
	v_cvt_f32_ubyte3_e32 v85, v59
	v_cvt_f32_ubyte2_e32 v84, v59
	v_pk_fma_f32 v[58:59], v[196:197], v[84:85], v[66:67] op_sel_hi:[0,1,1]
; DI void phase11b(const Params& P, char* smem_all) {
;     ...
;   auto reduce_store = [&](const uint4 (&v)[16], const float (&w)[16], int t) {
;     typedef float f2 __attribute__((ext_vector_type(2)));
;     f2 acc[8]; float wl = 0.f;
; #pragma unroll
;     for (int k = 0; k < 8; ++k) acc[k] = f2{0.f, 0.f};
; #pragma unroll
;     for (int r = 0; r < 16; ++r) {
;       wl += w[r];
;       const f2 w2 = f2{w[r], w[r]};
;       const unsigned vw[4] = {v[r].x, v[r].y, v[r].z, v[r].w};
; #pragma unroll
;       for (int k = 0; k < 4; ++k) {
;         acc[2 * k + 0] = __builtin_elementwise_fma(w2, f2{(float)(vw[k] & 0xffu), (float)((vw[k] >> 8) & 0xffu)}, acc[2 * k + 0]);
;         acc[2 * k + 1] = __builtin_elementwise_fma(w2, f2{(float)((vw[k] >> 16) & 0xffu), (float)(vw[k] >> 24)}, acc[2 * k + 1]);
;       }
;     }
;     const float rsum = dpp_row_sum_f(wl);
;     const float wsum = (__int_as_float(__builtin_amdgcn_readlane(__float_as_int(rsum), 0)) + __int_as_float(__builtin_amdgcn_readlane(__float_as_int(rsum), 16)) +
;                         __int_as_float(__builtin_amdgcn_readlane(__float_as_int(rsum), 32)) + __int_as_float(__builtin_amdgcn_readlane(__float_as_int(rsum), 48))) * 0.125f;
	v_cvt_f32_ubyte1_e32 v67, v52
	v_cvt_f32_ubyte0_e32 v66, v52
	v_pk_fma_f32 v[66:67], v[196:197], v[66:67], v[70:71] op_sel:[1,0,0]
	v_cvt_f32_ubyte3_e32 v71, v52
	v_cvt_f32_ubyte2_e32 v70, v52
	v_cvt_f32_ubyte3_e32 v85, v53
	v_cvt_f32_ubyte2_e32 v84, v53
	v_pk_fma_f32 v[70:71], v[196:197], v[70:71], v[78:79] op_sel:[1,0,0]
	v_cvt_f32_ubyte1_e32 v79, v53
	v_cvt_f32_ubyte0_e32 v78, v53
	v_pk_fma_f32 v[52:53], v[196:197], v[84:85], v[56:57] op_sel:[1,0,0]
	v_cvt_f32_ubyte1_e32 v57, v54
	v_cvt_f32_ubyte0_e32 v56, v54
	v_pk_fma_f32 v[56:57], v[196:197], v[56:57], v[64:65] op_sel:[1,0,0]
	v_cvt_f32_ubyte3_e32 v65, v54
	v_cvt_f32_ubyte2_e32 v64, v54
	v_pk_fma_f32 v[64:65], v[196:197], v[64:65], v[68:69] op_sel:[1,0,0]
	v_cvt_f32_ubyte1_e32 v69, v55
	v_cvt_f32_ubyte0_e32 v68, v55
	v_pk_fma_f32 v[68:69], v[196:197], v[68:69], v[76:77] op_sel:[1,0,0]
	v_cvt_f32_ubyte3_e32 v77, v55
	v_cvt_f32_ubyte2_e32 v76, v55
	v_pk_fma_f32 v[54:55], v[196:197], v[76:77], v[58:59] op_sel:[1,0,0]
	v_cvt_f32_ubyte1_e32 v59, v32
	v_cvt_f32_ubyte0_e32 v58, v32
	v_pk_fma_f32 v[58:59], v[198:199], v[58:59], v[66:67] op_sel_hi:[0,1,1]
	v_cvt_f32_ubyte3_e32 v67, v32
	v_cvt_f32_ubyte2_e32 v66, v32
	v_cvt_f32_ubyte3_e32 v77, v33
	v_cvt_f32_ubyte2_e32 v76, v33
	v_pk_fma_f32 v[66:67], v[198:199], v[66:67], v[70:71] op_sel_hi:[0,1,1]
	v_cvt_f32_ubyte1_e32 v71, v33
	v_cvt_f32_ubyte0_e32 v70, v33
	v_pk_fma_f32 v[32:33], v[198:199], v[76:77], v[52:53] op_sel_hi:[0,1,1]
	v_cvt_f32_ubyte1_e32 v53, v34
	v_cvt_f32_ubyte0_e32 v52, v34
	v_pk_fma_f32 v[52:53], v[198:199], v[52:53], v[56:57] op_sel_hi:[0,1,1]
	v_cvt_f32_ubyte3_e32 v57, v34
	v_cvt_f32_ubyte2_e32 v56, v34
	v_pk_fma_f32 v[56:57], v[198:199], v[56:57], v[64:65] op_sel_hi:[0,1,1]
	v_cvt_f32_ubyte1_e32 v65, v35
	v_cvt_f32_ubyte0_e32 v64, v35
	v_pk_fma_f32 v[64:65], v[198:199], v[64:65], v[68:69] op_sel_hi:[0,1,1]
	v_cvt_f32_ubyte3_e32 v69, v35
	v_cvt_f32_ubyte2_e32 v68, v35
	v_pk_fma_f32 v[34:35], v[198:199], v[68:69], v[54:55] op_sel_hi:[0,1,1]
	v_cvt_f32_ubyte1_e32 v55, v28
	v_cvt_f32_ubyte0_e32 v54, v28
	v_pk_fma_f32 v[54:55], v[198:199], v[54:55], v[58:59] op_sel:[1,0,0]
	v_cvt_f32_ubyte3_e32 v59, v28
	v_cvt_f32_ubyte2_e32 v58, v28
	v_cvt_f32_ubyte3_e32 v69, v29
	v_cvt_f32_ubyte2_e32 v68, v29
	v_pk_fma_f32 v[58:59], v[198:199], v[58:59], v[66:67] op_sel:[1,0,0]
	v_cvt_f32_ubyte1_e32 v67, v29
	v_cvt_f32_ubyte0_e32 v66, v29
	v_pk_fma_f32 v[28:29], v[198:199], v[68:69], v[32:33] op_sel:[1,0,0]
	v_cvt_f32_ubyte1_e32 v33, v30
	v_cvt_f32_ubyte0_e32 v32, v30
	v_add_f32_e32 v180, 0, v204
	v_pk_fma_f32 v[32:33], v[198:199], v[32:33], v[52:53] op_sel:[1,0,0]
	v_cvt_f32_ubyte3_e32 v53, v30
	v_cvt_f32_ubyte2_e32 v52, v30
	v_add_f32_e32 v144, v205, v180
	v_pk_fma_f32 v[52:53], v[198:199], v[52:53], v[56:57] op_sel:[1,0,0]
	v_cvt_f32_ubyte1_e32 v57, v31
	v_cvt_f32_ubyte0_e32 v56, v31
	v_add_f32_e32 v132, v206, v144
	v_pk_fma_f32 v[56:57], v[198:199], v[56:57], v[64:65] op_sel:[1,0,0]
	v_cvt_f32_ubyte3_e32 v65, v31
	v_cvt_f32_ubyte2_e32 v64, v31
	v_add_f32_e32 v128, v207, v132
	v_pk_fma_f32 v[30:31], v[198:199], v[64:65], v[34:35] op_sel:[1,0,0]
	v_cvt_f32_ubyte1_e32 v35, v20
	v_cvt_f32_ubyte0_e32 v34, v20
	v_add_f32_e32 v120, v200, v128
	v_pk_fma_f32 v[34:35], v[168:169], v[34:35], v[54:55] op_sel_hi:[0,1,1]
	v_cvt_f32_ubyte3_e32 v55, v20
	v_cvt_f32_ubyte2_e32 v54, v20
	v_cvt_f32_ubyte3_e32 v65, v21
	v_cvt_f32_ubyte2_e32 v64, v21
	v_add_f32_e32 v112, v201, v120
	v_pk_fma_f32 v[54:55], v[168:169], v[54:55], v[58:59] op_sel_hi:[0,1,1]
	v_cvt_f32_ubyte1_e32 v59, v21
	v_cvt_f32_ubyte0_e32 v58, v21
	v_pk_fma_f32 v[20:21], v[168:169], v[64:65], v[28:29] op_sel_hi:[0,1,1]
	v_cvt_f32_ubyte1_e32 v29, v22
	v_cvt_f32_ubyte0_e32 v28, v22
	v_add_f32_e32 v108, v202, v112
	v_pk_fma_f32 v[28:29], v[168:169], v[28:29], v[32:33] op_sel_hi:[0,1,1]
	v_cvt_f32_ubyte3_e32 v33, v22
	v_cvt_f32_ubyte2_e32 v32, v22
	v_add_f32_e32 v100, v203, v108
	v_pk_fma_f32 v[32:33], v[168:169], v[32:33], v[52:53] op_sel_hi:[0,1,1]
	v_cvt_f32_ubyte1_e32 v53, v23
	v_cvt_f32_ubyte0_e32 v52, v23
	v_add_f32_e32 v98, v196, v100
	v_pk_fma_f32 v[52:53], v[168:169], v[52:53], v[56:57] op_sel_hi:[0,1,1]
	v_cvt_f32_ubyte3_e32 v57, v23
	v_cvt_f32_ubyte2_e32 v56, v23
	v_add_f32_e32 v84, v197, v98
	v_pk_fma_f32 v[22:23], v[168:169], v[56:57], v[30:31] op_sel_hi:[0,1,1]
	v_cvt_f32_ubyte1_e32 v31, v16
	v_cvt_f32_ubyte0_e32 v30, v16
	v_pk_fma_f32 v[78:79], v[196:197], v[78:79], v[86:87] op_sel:[1,0,0]
	v_add_f32_e32 v76, v198, v84
	v_pk_fma_f32 v[30:31], v[168:169], v[30:31], v[34:35] op_sel:[1,0,0]
	v_cvt_f32_ubyte3_e32 v35, v16
	v_cvt_f32_ubyte2_e32 v34, v16
	v_pk_fma_f32 v[70:71], v[198:199], v[70:71], v[78:79] op_sel_hi:[0,1,1]
	v_add_f32_e32 v68, v199, v76
	v_pk_fma_f32 v[34:35], v[168:169], v[34:35], v[54:55] op_sel:[1,0,0]
	v_cvt_f32_ubyte1_e32 v55, v17
	v_cvt_f32_ubyte0_e32 v54, v17
	v_cvt_f32_ubyte3_e32 v57, v17
	v_cvt_f32_ubyte2_e32 v56, v17
	v_cvt_f32_ubyte1_e32 v17, v18
	v_cvt_f32_ubyte0_e32 v16, v18
	v_mov_b32_e32 v226, v225
	v_pk_fma_f32 v[66:67], v[198:199], v[66:67], v[70:71] op_sel:[1,0,0]
	v_add_f32_e32 v64, v168, v68
	v_pk_fma_f32 v[28:29], v[168:169], v[16:17], v[28:29] op_sel:[1,0,0]
	v_cvt_f32_ubyte3_e32 v17, v18
	v_cvt_f32_ubyte2_e32 v16, v18
	v_add_u32_e32 v225, s2, v226
	v_pk_fma_f32 v[58:59], v[168:169], v[58:59], v[66:67] op_sel_hi:[0,1,1]
	v_pk_fma_f32 v[32:33], v[168:169], v[16:17], v[32:33] op_sel:[1,0,0]
	v_cvt_f32_ubyte1_e32 v17, v19
	v_cvt_f32_ubyte0_e32 v16, v19
	v_add_f32_e32 v70, v169, v64
	v_cvt_f32_ubyte3_e32 v65, v8
	v_cvt_f32_ubyte2_e32 v64, v8
	v_cmp_gt_i32_e32 vcc, s14, v225
	v_pk_fma_f32 v[54:55], v[168:169], v[54:55], v[58:59] op_sel:[1,0,0]
; DI void phase11b(const Params& P, char* smem_all) {
;     ...
;     const float rsum = dpp_row_sum_f(wl);
;     const float wsum = (__int_as_float(__builtin_amdgcn_readlane(__float_as_int(rsum), 0)) + __int_as_float(__builtin_amdgcn_readlane(__float_as_int(rsum), 16)) +
;                         __int_as_float(__builtin_amdgcn_readlane(__float_as_int(rsum), 32)) + __int_as_float(__builtin_amdgcn_readlane(__float_as_int(rsum), 48))) * 0.125f;
; #pragma unroll
;     for (int k = 0; k < 4; ++k) *reinterpret_cast<float4*>(red + g8 * 128 + (lane & 7) * 16 + 4 * k) = make_float4(acc[2 * k][0], acc[2 * k][1], acc[2 * k + 1][0], acc[2 * k + 1][1]);
;     float2 s = make_float2(0.f, 0.f);
; #pragma unroll
;     for (int g = 0; g < 8; ++g) { const float2 a = *reinterpret_cast<const float2*>(red + g * 128 + 2 * lane); s.x += a.x; s.y += a.y; }
;     h2 zo; zo[0] = (_Float16)(s.x - 128.f * wsum); zo[1] = (_Float16)(s.y - 128.f * wsum);
;     *reinterpret_cast<h2*>(Zp + (long)t * 1024 + j * 128 + 2 * lane) = zo;
;   };
;   auto clampt = [&](int t) { return t < NTOK ? t : wslot; };
;   uint4 vA[16], vB[16]; float wA[16], wB[16];
;   load_list(wslot); gather(vA, wA);
;   load_list(clampt(wslot + nw));
;   for (int t = wslot; t < NTOK; t += 2 * nw) {
;     gather(vB, wB);
;     load_list(clampt(t + 2 * nw));
;     reduce_store(vA, wA, t);
;     gather(vA, wA);
;     load_list(clampt(t + 3 * nw));
	v_pk_fma_f32 v[52:53], v[168:169], v[16:17], v[52:53] op_sel:[1,0,0]
	v_cvt_f32_ubyte3_e32 v17, v19
	v_cvt_f32_ubyte2_e32 v16, v19
	v_pk_fma_f32 v[34:35], v[170:171], v[64:65], v[34:35] op_sel_hi:[0,1,1]
	v_cvt_f32_ubyte1_e32 v65, v9
	v_cvt_f32_ubyte0_e32 v64, v9
	global_load_dwordx4 v[80:83], v252, s[26:27]
	global_load_dwordx4 v[72:75], v253, s[26:27]
	v_cndmask_b32_e32 v36, v212, v225, vcc
	v_pk_fma_f32 v[56:57], v[168:169], v[56:57], v[20:21] op_sel:[1,0,0]
	v_pk_fma_f32 v[58:59], v[168:169], v[16:17], v[22:23] op_sel:[1,0,0]
	v_cvt_f32_ubyte1_e32 v17, v8
	v_cvt_f32_ubyte0_e32 v16, v8
	v_pk_fma_f32 v[54:55], v[170:171], v[64:65], v[54:55] op_sel_hi:[0,1,1]
	v_cvt_f32_ubyte3_e32 v65, v9
	v_cvt_f32_ubyte2_e32 v64, v9
	v_cvt_f32_ubyte1_e32 v9, v10
	v_cvt_f32_ubyte0_e32 v8, v10
	v_ashrrev_i32_e32 v37, 31, v36
	v_pk_fma_f32 v[56:57], v[170:171], v[64:65], v[56:57] op_sel_hi:[0,1,1]
	v_pk_fma_f32 v[64:65], v[170:171], v[8:9], v[28:29] op_sel_hi:[0,1,1]
	v_cvt_f32_ubyte3_e32 v9, v10
	v_cvt_f32_ubyte2_e32 v8, v10
	v_lshlrev_b64 v[36:37], 9, v[36:37]
	v_pk_fma_f32 v[66:67], v[170:171], v[8:9], v[32:33] op_sel_hi:[0,1,1]
	v_cvt_f32_ubyte1_e32 v9, v11
	v_cvt_f32_ubyte0_e32 v8, v11
	v_lshl_add_u64 v[96:97], v[216:217], 0, v[36:37]
	v_lshl_add_u64 v[48:49], v[218:219], 0, v[36:37]
	v_pk_fma_f32 v[68:69], v[170:171], v[8:9], v[52:53] op_sel_hi:[0,1,1]
	v_cvt_f32_ubyte3_e32 v9, v11
	v_cvt_f32_ubyte2_e32 v8, v11
	v_cvt_f32_ubyte3_e32 v11, v4
	v_cvt_f32_ubyte2_e32 v10, v4
	global_load_dwordx4 v[36:39], v[48:49], off offset:48
	global_load_dwordx4 v[40:43], v[48:49], off offset:32
	global_load_dwordx4 v[44:47], v[48:49], off offset:16
	s_nop 0
	global_load_dwordx4 v[48:51], v[48:49], off
	v_pk_fma_f32 v[30:31], v[170:171], v[16:17], v[30:31] op_sel_hi:[0,1,1]
	global_load_dwordx4 v[16:19], v[96:97], off offset:16
	global_load_dwordx4 v[20:23], v[96:97], off
	v_pk_fma_f32 v[10:11], v[170:171], v[10:11], v[34:35] op_sel:[1,0,0]
	global_load_dwordx4 v[108:111], v[96:97], off offset:48
	global_load_dwordx4 v[32:35], v[96:97], off offset:32
	v_pk_fma_f32 v[58:59], v[170:171], v[8:9], v[58:59] op_sel_hi:[0,1,1]
	v_cvt_f32_ubyte1_e32 v9, v4
	v_cvt_f32_ubyte0_e32 v8, v4
	v_pk_fma_f32 v[8:9], v[170:171], v[8:9], v[30:31] op_sel:[1,0,0]
	v_cvt_f32_ubyte1_e32 v29, v5
	v_cvt_f32_ubyte0_e32 v28, v5
	v_cvt_f32_ubyte3_e32 v31, v5
	v_cvt_f32_ubyte2_e32 v30, v5
	v_cvt_f32_ubyte1_e32 v5, v6
	v_cvt_f32_ubyte0_e32 v4, v6
	v_add_f32_e32 v70, v170, v70
	v_pk_fma_f32 v[30:31], v[170:171], v[30:31], v[56:57] op_sel:[1,0,0]
	v_pk_fma_f32 v[52:53], v[170:171], v[4:5], v[64:65] op_sel:[1,0,0]
	v_cvt_f32_ubyte3_e32 v5, v6
	v_cvt_f32_ubyte2_e32 v4, v6
	v_cvt_f32_ubyte3_e32 v57, v7
	v_cvt_f32_ubyte2_e32 v56, v7
	v_pk_fma_f32 v[28:29], v[170:171], v[28:29], v[54:55] op_sel:[1,0,0]
	v_pk_fma_f32 v[54:55], v[170:171], v[4:5], v[66:67] op_sel:[1,0,0]
	v_cvt_f32_ubyte1_e32 v5, v7
	v_cvt_f32_ubyte0_e32 v4, v7
	v_pk_fma_f32 v[6:7], v[170:171], v[56:57], v[58:59] op_sel:[1,0,0]
	v_add_f32_e32 v56, v171, v70
	v_pk_fma_f32 v[4:5], v[170:171], v[4:5], v[68:69] op_sel:[1,0,0]
	ds_write_b128 v213, v[8:11]
	ds_write_b128 v213, v[28:31] offset:16
	ds_write_b128 v213, v[52:55] offset:32
	ds_write_b128 v213, v[4:7] offset:48
	v_add_f32_dpp v56, v56, v56 quad_perm:[1,0,3,2] row_mask:0xf bank_mask:0xf bound_ctrl:1
	ds_read2st64_b64 v[28:31], v224 offset0:4 offset1:5
	s_nop 0
	v_add_f32_dpp v56, v56, v56 quad_perm:[2,3,0,1] row_mask:0xf bank_mask:0xf bound_ctrl:1
	s_nop 1
	v_add_f32_dpp v56, v56, v56 row_half_mirror row_mask:0xf bank_mask:0xf bound_ctrl:1
	s_nop 1
	v_add_f32_dpp v56, v56, v56 row_mirror row_mask:0xf bank_mask:0xf bound_ctrl:1
	s_nop 0
	v_readlane_b32 s12, v56, 16
	v_readlane_b32 s0, v56, 0
	v_readlane_b32 s1, v56, 32
	v_mov_b32_e32 v4, s12
	v_add_f32_e32 v4, s0, v4
	v_readlane_b32 s13, v56, 48
	v_add_f32_e32 v8, s1, v4
	ds_read2st64_b64 v[4:7], v224 offset1:1
	v_add_f32_e32 v8, s13, v8
	v_mul_f32_e32 v8, 0x3e000000, v8
	v_mul_f32_e32 v52, 0x43000000, v8
	ds_read2st64_b64 v[8:11], v224 offset0:2 offset1:3
	s_waitcnt lgkmcnt(1)
	v_pk_add_f32 v[4:5], v[4:5], 0 op_sel_hi:[1,0]
	s_nop 0
	v_pk_add_f32 v[54:55], v[4:5], v[6:7]
	ds_read2st64_b64 v[4:7], v224 offset0:6 offset1:7
	s_waitcnt lgkmcnt(1)
	v_pk_add_f32 v[8:9], v[54:55], v[8:9]
	s_nop 0
	v_pk_add_f32 v[8:9], v[8:9], v[10:11]
	s_waitcnt vmcnt(2)
	v_pk_add_f32 v[8:9], v[8:9], v[28:29]
	v_lshl_add_u32 v228, v20, 7, v227
	v_pk_add_f32 v[8:9], v[8:9], v[30:31]
	v_lshl_add_u32 v229, v21, 7, v227
	s_waitcnt lgkmcnt(0)
	v_pk_add_f32 v[4:5], v[8:9], v[4:5]
	v_lshl_add_u32 v230, v22, 7, v227
	v_pk_add_f32 v[4:5], v[4:5], v[6:7]
	v_lshl_add_u32 v231, v23, 7, v227
	v_pk_add_f32 v[4:5], v[4:5], v[52:53] op_sel_hi:[1,0] neg_lo:[0,1] neg_hi:[0,1]
	v_lshl_add_u32 v232, v16, 7, v227
	v_cvt_pk_f16_f32 v54, v4, v5
	v_lshl_add_u32 v233, v17, 7, v227
	v_lshl_add_u32 v234, v18, 7, v227
	v_lshl_add_u32 v235, v19, 7, v227
	s_waitcnt vmcnt(0)
	v_lshl_add_u32 v236, v32, 7, v227
	v_lshl_add_u32 v237, v33, 7, v227
	v_lshl_add_u32 v238, v34, 7, v227
	v_lshl_add_u32 v239, v35, 7, v227
	v_lshl_add_u32 v240, v108, 7, v227
	v_lshl_add_u32 v241, v109, 7, v227
	v_lshl_add_u32 v242, v110, 7, v227
	v_lshl_add_u32 v243, v111, 7, v227
	global_store_dword v[222:223], v54, off
	global_load_dwordx4 v[144:147], v228, s[26:27]
	global_load_dwordx4 v[132:135], v229, s[26:27]
	global_load_dwordx4 v[112:115], v230, s[26:27]
	global_load_dwordx4 v[100:103], v231, s[26:27]
	global_load_dwordx4 v[84:87], v232, s[26:27]
	global_load_dwordx4 v[76:79], v233, s[26:27]
	global_load_dwordx4 v[68:71], v234, s[26:27]
	global_load_dwordx4 v[64:67], v235, s[26:27]
	global_load_dwordx4 v[56:59], v236, s[26:27]
	global_load_dwordx4 v[52:55], v237, s[26:27]
	global_load_dwordx4 v[32:35], v238, s[26:27]
	global_load_dwordx4 v[28:31], v239, s[26:27]
	global_load_dwordx4 v[20:23], v240, s[26:27]
	global_load_dwordx4 v[16:19], v241, s[26:27]
	global_load_dwordx4 v[8:11], v242, s[26:27]
	global_load_dwordx4 v[4:7], v243, s[26:27]
	v_add_u32_e32 v96, s5, v226
	v_cmp_gt_i32_e32 vcc, s14, v96
	s_nop 1
	v_cndmask_b32_e32 v96, v212, v96, vcc
	v_ashrrev_i32_e32 v97, 31, v96
	v_lshlrev_b64 v[168:169], 9, v[96:97]
	v_lshl_add_u64 v[128:129], v[216:217], 0, v[168:169]
	v_lshl_add_u64 v[168:169], v[218:219], 0, v[168:169]
	s_nop 0
	global_load_dwordx4 v[96:99], v[128:129], off offset:48
	global_load_dwordx4 v[108:111], v[128:129], off offset:32
	global_load_dwordx4 v[120:123], v[128:129], off offset:16
	s_nop 0
	global_load_dwordx4 v[128:131], v[128:129], off
	s_nop 0
	global_load_dwordx4 v[180:183], v[168:169], off offset:48
	global_load_dwordx4 v[184:187], v[168:169], off offset:32
	global_load_dwordx4 v[188:191], v[168:169], off offset:16
	global_load_dwordx4 v[192:195], v[168:169], off
	v_add_u32_e32 v168, s4, v226
	v_cmp_lt_i32_e32 vcc, s3, v225
	v_cmp_gt_i32_e64 s[0:1], s14, v168
	s_and_saveexec_b64 s[12:13], s[0:1]
	s_cbranch_execz .LBB0_1579
; DI void phase11b(const Params& P, char* smem_all) {
;     ...
;     for (int r = 0; r < 16; ++r) {
;       wl += w[r];
;       const f2 w2 = f2{w[r], w[r]};
;       const unsigned vw[4] = {v[r].x, v[r].y, v[r].z, v[r].w};
; #pragma unroll
;       for (int k = 0; k < 4; ++k) {
;         acc[2 * k + 0] = __builtin_elementwise_fma(w2, f2{(float)(vw[k] & 0xffu), (float)((vw[k] >> 8) & 0xffu)}, acc[2 * k + 0]);
;         acc[2 * k + 1] = __builtin_elementwise_fma(w2, f2{(float)((vw[k] >> 16) & 0xffu), (float)(vw[k] >> 24)}, acc[2 * k + 1]);
;       }
;     }
	v_cvt_f32_ubyte1_e32 v171, v176
	v_cvt_f32_ubyte0_e32 v170, v176
	v_cvt_f32_ubyte3_e32 v201, v177
	v_cvt_f32_ubyte2_e32 v200, v177
	v_cvt_f32_ubyte3_e32 v207, v179
	v_cvt_f32_ubyte2_e32 v206, v179
	v_pk_fma_f32 v[170:171], v[60:61], v[170:171], 0 op_sel_hi:[0,1,0]
	v_cvt_f32_ubyte3_e32 v197, v176
	v_cvt_f32_ubyte2_e32 v196, v176
	v_cvt_f32_ubyte1_e32 v199, v177
	v_cvt_f32_ubyte0_e32 v198, v177
	v_pk_fma_f32 v[176:177], v[60:61], v[200:201], 0 op_sel_hi:[0,1,0]
	v_cvt_f32_ubyte1_e32 v201, v178
	v_cvt_f32_ubyte0_e32 v200, v178
	v_cvt_f32_ubyte3_e32 v203, v178
	v_cvt_f32_ubyte2_e32 v202, v178
	v_cvt_f32_ubyte1_e32 v205, v179
	v_cvt_f32_ubyte0_e32 v204, v179
	v_pk_fma_f32 v[178:179], v[60:61], v[206:207], 0 op_sel_hi:[0,1,0]
	v_cvt_f32_ubyte1_e32 v207, v172
	v_cvt_f32_ubyte0_e32 v206, v172
	v_pk_fma_f32 v[196:197], v[60:61], v[196:197], 0 op_sel_hi:[0,1,0]
	v_pk_fma_f32 v[170:171], v[60:61], v[206:207], v[170:171] op_sel:[1,0,0]
	v_cvt_f32_ubyte3_e32 v207, v172
	v_cvt_f32_ubyte2_e32 v206, v172
	v_pk_fma_f32 v[198:199], v[60:61], v[198:199], 0 op_sel_hi:[0,1,0]
	v_pk_fma_f32 v[196:197], v[60:61], v[206:207], v[196:197] op_sel:[1,0,0]
	v_cvt_f32_ubyte1_e32 v207, v173
	v_cvt_f32_ubyte0_e32 v206, v173
	v_pk_fma_f32 v[198:199], v[60:61], v[206:207], v[198:199] op_sel:[1,0,0]
	v_cvt_f32_ubyte3_e32 v207, v173
	v_cvt_f32_ubyte2_e32 v206, v173
	v_pk_fma_f32 v[200:201], v[60:61], v[200:201], 0 op_sel_hi:[0,1,0]
	v_pk_fma_f32 v[172:173], v[60:61], v[206:207], v[176:177] op_sel:[1,0,0]
	v_cvt_f32_ubyte1_e32 v177, v174
	v_cvt_f32_ubyte0_e32 v176, v174
	v_pk_fma_f32 v[202:203], v[60:61], v[202:203], 0 op_sel_hi:[0,1,0]
	v_pk_fma_f32 v[176:177], v[60:61], v[176:177], v[200:201] op_sel:[1,0,0]
	v_cvt_f32_ubyte3_e32 v201, v174
	v_cvt_f32_ubyte2_e32 v200, v174
	v_pk_fma_f32 v[204:205], v[60:61], v[204:205], 0 op_sel_hi:[0,1,0]
	v_pk_fma_f32 v[200:201], v[60:61], v[200:201], v[202:203] op_sel:[1,0,0]
	v_cvt_f32_ubyte1_e32 v203, v175
	v_cvt_f32_ubyte0_e32 v202, v175
	v_add_f32_e32 v169, 0, v60
	v_pk_fma_f32 v[202:203], v[60:61], v[202:203], v[204:205] op_sel:[1,0,0]
	v_cvt_f32_ubyte3_e32 v205, v175
	v_cvt_f32_ubyte2_e32 v204, v175
	v_pk_fma_f32 v[174:175], v[60:61], v[204:205], v[178:179] op_sel:[1,0,0]
	v_add_f32_e32 v169, v61, v169
	v_cvt_f32_ubyte1_e32 v61, v164
	v_cvt_f32_ubyte0_e32 v60, v164
	v_pk_fma_f32 v[60:61], v[62:63], v[60:61], v[170:171] op_sel_hi:[0,1,1]
	v_cvt_f32_ubyte3_e32 v171, v164
	v_cvt_f32_ubyte2_e32 v170, v164
	v_pk_fma_f32 v[170:171], v[62:63], v[170:171], v[196:197] op_sel_hi:[0,1,1]
	v_cvt_f32_ubyte1_e32 v179, v165
	v_cvt_f32_ubyte0_e32 v178, v165
	v_cvt_f32_ubyte3_e32 v197, v165
	v_cvt_f32_ubyte2_e32 v196, v165
	v_pk_fma_f32 v[178:179], v[62:63], v[178:179], v[198:199] op_sel_hi:[0,1,1]
	v_pk_fma_f32 v[164:165], v[62:63], v[196:197], v[172:173] op_sel_hi:[0,1,1]
	v_cvt_f32_ubyte1_e32 v173, v166
	v_cvt_f32_ubyte0_e32 v172, v166
	v_cvt_f32_ubyte3_e32 v199, v167
	v_cvt_f32_ubyte2_e32 v198, v167
	v_pk_fma_f32 v[172:173], v[62:63], v[172:173], v[176:177] op_sel_hi:[0,1,1]
	v_cvt_f32_ubyte3_e32 v177, v166
	v_cvt_f32_ubyte2_e32 v176, v166
	v_cvt_f32_ubyte1_e32 v197, v167
	v_cvt_f32_ubyte0_e32 v196, v167
	v_pk_fma_f32 v[166:167], v[62:63], v[198:199], v[174:175] op_sel_hi:[0,1,1]
	v_cvt_f32_ubyte1_e32 v175, v160
	v_cvt_f32_ubyte0_e32 v174, v160
	v_pk_fma_f32 v[60:61], v[62:63], v[174:175], v[60:61] op_sel:[1,0,0]
	v_cvt_f32_ubyte3_e32 v175, v160
	v_cvt_f32_ubyte2_e32 v174, v160
	v_pk_fma_f32 v[170:171], v[62:63], v[174:175], v[170:171] op_sel:[1,0,0]
	v_cvt_f32_ubyte1_e32 v175, v161
	v_cvt_f32_ubyte0_e32 v174, v161
	v_pk_fma_f32 v[174:175], v[62:63], v[174:175], v[178:179] op_sel:[1,0,0]
	v_cvt_f32_ubyte3_e32 v179, v161
	v_cvt_f32_ubyte2_e32 v178, v161
	v_pk_fma_f32 v[160:161], v[62:63], v[178:179], v[164:165] op_sel:[1,0,0]
	v_cvt_f32_ubyte1_e32 v165, v162
	v_cvt_f32_ubyte0_e32 v164, v162
	v_pk_fma_f32 v[176:177], v[62:63], v[176:177], v[200:201] op_sel_hi:[0,1,1]
	v_pk_fma_f32 v[164:165], v[62:63], v[164:165], v[172:173] op_sel:[1,0,0]
	v_cvt_f32_ubyte3_e32 v173, v162
	v_cvt_f32_ubyte2_e32 v172, v162
	v_pk_fma_f32 v[196:197], v[62:63], v[196:197], v[202:203] op_sel_hi:[0,1,1]
	v_add_f32_e32 v169, v62, v169
	v_pk_fma_f32 v[172:173], v[62:63], v[172:173], v[176:177] op_sel:[1,0,0]
	v_cvt_f32_ubyte1_e32 v177, v163
	v_cvt_f32_ubyte0_e32 v176, v163
	v_cvt_f32_ubyte3_e32 v179, v163
	v_cvt_f32_ubyte2_e32 v178, v163
	v_pk_fma_f32 v[176:177], v[62:63], v[176:177], v[196:197] op_sel:[1,0,0]
	v_pk_fma_f32 v[162:163], v[62:63], v[178:179], v[166:167] op_sel:[1,0,0]
	v_add_f32_e32 v169, v63, v169
	v_cvt_f32_ubyte1_e32 v63, v156
	v_cvt_f32_ubyte0_e32 v62, v156
	v_pk_fma_f32 v[60:61], v[24:25], v[62:63], v[60:61] op_sel_hi:[0,1,1]
	v_cvt_f32_ubyte3_e32 v63, v156
	v_cvt_f32_ubyte2_e32 v62, v156
	v_pk_fma_f32 v[62:63], v[24:25], v[62:63], v[170:171] op_sel_hi:[0,1,1]
	v_cvt_f32_ubyte3_e32 v171, v157
	v_cvt_f32_ubyte2_e32 v170, v157
	v_cvt_f32_ubyte1_e32 v167, v157
	v_cvt_f32_ubyte0_e32 v166, v157
	v_pk_fma_f32 v[156:157], v[24:25], v[170:171], v[160:161] op_sel_hi:[0,1,1]
	v_cvt_f32_ubyte1_e32 v161, v158
	v_cvt_f32_ubyte0_e32 v160, v158
	v_pk_fma_f32 v[160:161], v[24:25], v[160:161], v[164:165] op_sel_hi:[0,1,1]
	v_cvt_f32_ubyte3_e32 v165, v158
	v_cvt_f32_ubyte2_e32 v164, v158
	v_pk_fma_f32 v[164:165], v[24:25], v[164:165], v[172:173] op_sel_hi:[0,1,1]
	v_cvt_f32_ubyte3_e32 v173, v159
	v_cvt_f32_ubyte2_e32 v172, v159
	v_cvt_f32_ubyte1_e32 v171, v159
	v_cvt_f32_ubyte0_e32 v170, v159
	v_pk_fma_f32 v[158:159], v[24:25], v[172:173], v[162:163] op_sel_hi:[0,1,1]
	v_cvt_f32_ubyte1_e32 v163, v152
	v_cvt_f32_ubyte0_e32 v162, v152
; DI void phase11b(const Params& P, char* smem_all) {
;     ...
;     for (int r = 0; r < 16; ++r) {
;       wl += w[r];
;       const f2 w2 = f2{w[r], w[r]};
;       const unsigned vw[4] = {v[r].x, v[r].y, v[r].z, v[r].w};
; #pragma unroll
;       for (int k = 0; k < 4; ++k) {
;         acc[2 * k + 0] = __builtin_elementwise_fma(w2, f2{(float)(vw[k] & 0xffu), (float)((vw[k] >> 8) & 0xffu)}, acc[2 * k + 0]);
;         acc[2 * k + 1] = __builtin_elementwise_fma(w2, f2{(float)((vw[k] >> 16) & 0xffu), (float)(vw[k] >> 24)}, acc[2 * k + 1]);
;       }
;     }
	v_pk_fma_f32 v[60:61], v[24:25], v[162:163], v[60:61] op_sel:[1,0,0]
	v_cvt_f32_ubyte3_e32 v163, v152
	v_cvt_f32_ubyte2_e32 v162, v152
	v_pk_fma_f32 v[166:167], v[24:25], v[166:167], v[174:175] op_sel_hi:[0,1,1]
	v_pk_fma_f32 v[62:63], v[24:25], v[162:163], v[62:63] op_sel:[1,0,0]
	v_cvt_f32_ubyte1_e32 v163, v153
	v_cvt_f32_ubyte0_e32 v162, v153
	v_pk_fma_f32 v[162:163], v[24:25], v[162:163], v[166:167] op_sel:[1,0,0]
	v_cvt_f32_ubyte3_e32 v167, v153
	v_cvt_f32_ubyte2_e32 v166, v153
	v_pk_fma_f32 v[152:153], v[24:25], v[166:167], v[156:157] op_sel:[1,0,0]
	v_cvt_f32_ubyte1_e32 v157, v154
	v_cvt_f32_ubyte0_e32 v156, v154
	v_pk_fma_f32 v[156:157], v[24:25], v[156:157], v[160:161] op_sel:[1,0,0]
	v_cvt_f32_ubyte3_e32 v161, v154
	v_cvt_f32_ubyte2_e32 v160, v154
	v_pk_fma_f32 v[170:171], v[24:25], v[170:171], v[176:177] op_sel_hi:[0,1,1]
	v_add_f32_e32 v169, v24, v169
	v_pk_fma_f32 v[160:161], v[24:25], v[160:161], v[164:165] op_sel:[1,0,0]
	v_cvt_f32_ubyte1_e32 v165, v155
	v_cvt_f32_ubyte0_e32 v164, v155
	v_cvt_f32_ubyte3_e32 v167, v155
	v_cvt_f32_ubyte2_e32 v166, v155
	v_pk_fma_f32 v[164:165], v[24:25], v[164:165], v[170:171] op_sel:[1,0,0]
	v_pk_fma_f32 v[154:155], v[24:25], v[166:167], v[158:159] op_sel:[1,0,0]
	v_add_f32_e32 v166, v25, v169
	v_cvt_f32_ubyte1_e32 v25, v148
	v_cvt_f32_ubyte0_e32 v24, v148
	v_pk_fma_f32 v[24:25], v[26:27], v[24:25], v[60:61] op_sel_hi:[0,1,1]
	v_cvt_f32_ubyte3_e32 v61, v148
	v_cvt_f32_ubyte2_e32 v60, v148
	v_cvt_f32_ubyte3_e32 v159, v149
	v_cvt_f32_ubyte2_e32 v158, v149
	v_pk_fma_f32 v[60:61], v[26:27], v[60:61], v[62:63] op_sel_hi:[0,1,1]
	v_cvt_f32_ubyte1_e32 v63, v149
	v_cvt_f32_ubyte0_e32 v62, v149
	v_pk_fma_f32 v[148:149], v[26:27], v[158:159], v[152:153] op_sel_hi:[0,1,1]
	v_cvt_f32_ubyte1_e32 v153, v150
	v_cvt_f32_ubyte0_e32 v152, v150
	v_pk_fma_f32 v[152:153], v[26:27], v[152:153], v[156:157] op_sel_hi:[0,1,1]
	v_cvt_f32_ubyte3_e32 v157, v150
	v_cvt_f32_ubyte2_e32 v156, v150
	v_pk_fma_f32 v[156:157], v[26:27], v[156:157], v[160:161] op_sel_hi:[0,1,1]
	v_cvt_f32_ubyte3_e32 v161, v151
	v_cvt_f32_ubyte2_e32 v160, v151
	v_cvt_f32_ubyte1_e32 v159, v151
	v_cvt_f32_ubyte0_e32 v158, v151
	v_pk_fma_f32 v[150:151], v[26:27], v[160:161], v[154:155] op_sel_hi:[0,1,1]
	v_cvt_f32_ubyte1_e32 v155, v140
	v_cvt_f32_ubyte0_e32 v154, v140
	v_pk_fma_f32 v[24:25], v[26:27], v[154:155], v[24:25] op_sel:[1,0,0]
	v_cvt_f32_ubyte3_e32 v155, v140
	v_cvt_f32_ubyte2_e32 v154, v140
	v_pk_fma_f32 v[62:63], v[26:27], v[62:63], v[162:163] op_sel_hi:[0,1,1]
	v_pk_fma_f32 v[60:61], v[26:27], v[154:155], v[60:61] op_sel:[1,0,0]
	v_cvt_f32_ubyte1_e32 v155, v141
	v_cvt_f32_ubyte0_e32 v154, v141
	v_pk_fma_f32 v[62:63], v[26:27], v[154:155], v[62:63] op_sel:[1,0,0]
	v_cvt_f32_ubyte3_e32 v155, v141
	v_cvt_f32_ubyte2_e32 v154, v141
	v_pk_fma_f32 v[140:141], v[26:27], v[154:155], v[148:149] op_sel:[1,0,0]
	v_cvt_f32_ubyte1_e32 v149, v142
	v_cvt_f32_ubyte0_e32 v148, v142
	v_pk_fma_f32 v[148:149], v[26:27], v[148:149], v[152:153] op_sel:[1,0,0]
	v_cvt_f32_ubyte3_e32 v153, v142
	v_cvt_f32_ubyte2_e32 v152, v142
	v_pk_fma_f32 v[158:159], v[26:27], v[158:159], v[164:165] op_sel_hi:[0,1,1]
	v_add_f32_e32 v160, v26, v166
	v_pk_fma_f32 v[152:153], v[26:27], v[152:153], v[156:157] op_sel:[1,0,0]
	v_cvt_f32_ubyte1_e32 v155, v143
	v_cvt_f32_ubyte0_e32 v154, v143
	v_cvt_f32_ubyte3_e32 v157, v143
	v_cvt_f32_ubyte2_e32 v156, v143
	v_pk_fma_f32 v[154:155], v[26:27], v[154:155], v[158:159] op_sel:[1,0,0]
	v_pk_fma_f32 v[142:143], v[26:27], v[156:157], v[150:151] op_sel:[1,0,0]
	v_add_f32_e32 v156, v27, v160
	v_cvt_f32_ubyte1_e32 v27, v136
	v_cvt_f32_ubyte0_e32 v26, v136
	v_pk_fma_f32 v[24:25], v[12:13], v[26:27], v[24:25] op_sel_hi:[0,1,1]
	v_cvt_f32_ubyte3_e32 v27, v136
	v_cvt_f32_ubyte2_e32 v26, v136
	v_pk_fma_f32 v[26:27], v[12:13], v[26:27], v[60:61] op_sel_hi:[0,1,1]
	v_cvt_f32_ubyte1_e32 v61, v137
	v_cvt_f32_ubyte0_e32 v60, v137
	v_pk_fma_f32 v[60:61], v[12:13], v[60:61], v[62:63] op_sel_hi:[0,1,1]
	v_cvt_f32_ubyte3_e32 v63, v137
	v_cvt_f32_ubyte2_e32 v62, v137
	v_cvt_f32_ubyte1_e32 v137, v138
	v_cvt_f32_ubyte0_e32 v136, v138
	v_cvt_f32_ubyte3_e32 v151, v139
	v_cvt_f32_ubyte2_e32 v150, v139
	v_pk_fma_f32 v[62:63], v[12:13], v[62:63], v[140:141] op_sel_hi:[0,1,1]
	v_pk_fma_f32 v[136:137], v[12:13], v[136:137], v[148:149] op_sel_hi:[0,1,1]
	v_cvt_f32_ubyte3_e32 v141, v138
	v_cvt_f32_ubyte2_e32 v140, v138
	v_cvt_f32_ubyte1_e32 v149, v139
	v_cvt_f32_ubyte0_e32 v148, v139
	v_pk_fma_f32 v[138:139], v[12:13], v[150:151], v[142:143] op_sel_hi:[0,1,1]
	v_cvt_f32_ubyte1_e32 v143, v124
	v_cvt_f32_ubyte0_e32 v142, v124
	v_pk_fma_f32 v[24:25], v[12:13], v[142:143], v[24:25] op_sel:[1,0,0]
	v_cvt_f32_ubyte3_e32 v143, v124
	v_cvt_f32_ubyte2_e32 v142, v124
	v_pk_fma_f32 v[26:27], v[12:13], v[142:143], v[26:27] op_sel:[1,0,0]
	v_cvt_f32_ubyte1_e32 v143, v125
	v_cvt_f32_ubyte0_e32 v142, v125
	v_pk_fma_f32 v[60:61], v[12:13], v[142:143], v[60:61] op_sel:[1,0,0]
	v_cvt_f32_ubyte3_e32 v143, v125
	v_cvt_f32_ubyte2_e32 v142, v125
	v_cvt_f32_ubyte1_e32 v125, v126
	v_cvt_f32_ubyte0_e32 v124, v126
	v_pk_fma_f32 v[140:141], v[12:13], v[140:141], v[152:153] op_sel_hi:[0,1,1]
	v_pk_fma_f32 v[124:125], v[12:13], v[124:125], v[136:137] op_sel:[1,0,0]
	v_cvt_f32_ubyte3_e32 v137, v126
	v_cvt_f32_ubyte2_e32 v136, v126
	v_pk_fma_f32 v[148:149], v[12:13], v[148:149], v[154:155] op_sel_hi:[0,1,1]
	v_add_f32_e32 v150, v12, v156
	v_pk_fma_f32 v[62:63], v[12:13], v[142:143], v[62:63] op_sel:[1,0,0]
	v_pk_fma_f32 v[136:137], v[12:13], v[136:137], v[140:141] op_sel:[1,0,0]
	v_cvt_f32_ubyte1_e32 v141, v127
	v_cvt_f32_ubyte0_e32 v140, v127
	v_cvt_f32_ubyte3_e32 v143, v127
	v_cvt_f32_ubyte2_e32 v142, v127
; DI void phase11b(const Params& P, char* smem_all) {
;     ...
;     for (int r = 0; r < 16; ++r) {
;       wl += w[r];
;       const f2 w2 = f2{w[r], w[r]};
;       const unsigned vw[4] = {v[r].x, v[r].y, v[r].z, v[r].w};
; #pragma unroll
;       for (int k = 0; k < 4; ++k) {
;         acc[2 * k + 0] = __builtin_elementwise_fma(w2, f2{(float)(vw[k] & 0xffu), (float)((vw[k] >> 8) & 0xffu)}, acc[2 * k + 0]);
;         acc[2 * k + 1] = __builtin_elementwise_fma(w2, f2{(float)((vw[k] >> 16) & 0xffu), (float)(vw[k] >> 24)}, acc[2 * k + 1]);
;       }
;     }
	v_pk_fma_f32 v[140:141], v[12:13], v[140:141], v[148:149] op_sel:[1,0,0]
	v_pk_fma_f32 v[126:127], v[12:13], v[142:143], v[138:139] op_sel:[1,0,0]
	v_add_f32_e32 v138, v13, v150
	v_cvt_f32_ubyte1_e32 v13, v116
	v_cvt_f32_ubyte0_e32 v12, v116
	v_pk_fma_f32 v[12:13], v[14:15], v[12:13], v[24:25] op_sel_hi:[0,1,1]
	v_cvt_f32_ubyte3_e32 v25, v116
	v_cvt_f32_ubyte2_e32 v24, v116
	v_pk_fma_f32 v[24:25], v[14:15], v[24:25], v[26:27] op_sel_hi:[0,1,1]
	v_cvt_f32_ubyte1_e32 v27, v117
	v_cvt_f32_ubyte0_e32 v26, v117
	v_pk_fma_f32 v[26:27], v[14:15], v[26:27], v[60:61] op_sel_hi:[0,1,1]
	v_cvt_f32_ubyte3_e32 v61, v117
	v_cvt_f32_ubyte2_e32 v60, v117
	v_cvt_f32_ubyte3_e32 v117, v118
	v_cvt_f32_ubyte2_e32 v116, v118
	v_pk_fma_f32 v[60:61], v[14:15], v[60:61], v[62:63] op_sel_hi:[0,1,1]
	v_cvt_f32_ubyte1_e32 v63, v118
	v_cvt_f32_ubyte0_e32 v62, v118
	v_pk_fma_f32 v[116:117], v[14:15], v[116:117], v[136:137] op_sel_hi:[0,1,1]
	v_cvt_f32_ubyte3_e32 v137, v119
	v_cvt_f32_ubyte2_e32 v136, v119
	v_pk_fma_f32 v[62:63], v[14:15], v[62:63], v[124:125] op_sel_hi:[0,1,1]
	v_cvt_f32_ubyte1_e32 v125, v119
	v_cvt_f32_ubyte0_e32 v124, v119
	v_pk_fma_f32 v[118:119], v[14:15], v[136:137], v[126:127] op_sel_hi:[0,1,1]
	v_cvt_f32_ubyte1_e32 v127, v104
	v_cvt_f32_ubyte0_e32 v126, v104
	v_pk_fma_f32 v[12:13], v[14:15], v[126:127], v[12:13] op_sel:[1,0,0]
	v_cvt_f32_ubyte3_e32 v127, v104
	v_cvt_f32_ubyte2_e32 v126, v104
	v_pk_fma_f32 v[24:25], v[14:15], v[126:127], v[24:25] op_sel:[1,0,0]
	v_cvt_f32_ubyte1_e32 v127, v105
	v_cvt_f32_ubyte0_e32 v126, v105
	v_pk_fma_f32 v[26:27], v[14:15], v[126:127], v[26:27] op_sel:[1,0,0]
	v_cvt_f32_ubyte3_e32 v127, v105
	v_cvt_f32_ubyte2_e32 v126, v105
	v_cvt_f32_ubyte1_e32 v105, v106
	v_cvt_f32_ubyte0_e32 v104, v106
	v_pk_fma_f32 v[62:63], v[14:15], v[104:105], v[62:63] op_sel:[1,0,0]
	v_cvt_f32_ubyte3_e32 v105, v106
	v_cvt_f32_ubyte2_e32 v104, v106
	v_pk_fma_f32 v[124:125], v[14:15], v[124:125], v[140:141] op_sel_hi:[0,1,1]
	v_pk_fma_f32 v[104:105], v[14:15], v[104:105], v[116:117] op_sel:[1,0,0]
	v_cvt_f32_ubyte1_e32 v117, v107
	v_cvt_f32_ubyte0_e32 v116, v107
	v_add_f32_e32 v136, v14, v138
	v_pk_fma_f32 v[116:117], v[14:15], v[116:117], v[124:125] op_sel:[1,0,0]
	v_cvt_f32_ubyte3_e32 v125, v107
	v_cvt_f32_ubyte2_e32 v124, v107
	v_pk_fma_f32 v[60:61], v[14:15], v[126:127], v[60:61] op_sel:[1,0,0]
	v_pk_fma_f32 v[106:107], v[14:15], v[124:125], v[118:119] op_sel:[1,0,0]
	v_add_f32_e32 v118, v15, v136
	v_cvt_f32_ubyte1_e32 v15, v92
	v_cvt_f32_ubyte0_e32 v14, v92
	v_pk_fma_f32 v[12:13], v[0:1], v[14:15], v[12:13] op_sel_hi:[0,1,1]
	v_cvt_f32_ubyte3_e32 v15, v92
	v_cvt_f32_ubyte2_e32 v14, v92
	v_pk_fma_f32 v[14:15], v[0:1], v[14:15], v[24:25] op_sel_hi:[0,1,1]
	v_cvt_f32_ubyte1_e32 v25, v93
	v_cvt_f32_ubyte0_e32 v24, v93
	v_pk_fma_f32 v[24:25], v[0:1], v[24:25], v[26:27] op_sel_hi:[0,1,1]
	v_cvt_f32_ubyte3_e32 v27, v93
	v_cvt_f32_ubyte2_e32 v26, v93
	v_pk_fma_f32 v[26:27], v[0:1], v[26:27], v[60:61] op_sel_hi:[0,1,1]
	v_cvt_f32_ubyte1_e32 v61, v94
	v_cvt_f32_ubyte0_e32 v60, v94
	v_pk_fma_f32 v[60:61], v[0:1], v[60:61], v[62:63] op_sel_hi:[0,1,1]
	v_cvt_f32_ubyte3_e32 v63, v94
	v_cvt_f32_ubyte2_e32 v62, v94
	v_pk_fma_f32 v[62:63], v[0:1], v[62:63], v[104:105] op_sel_hi:[0,1,1]
	v_cvt_f32_ubyte3_e32 v105, v95
	v_cvt_f32_ubyte2_e32 v104, v95
	v_cvt_f32_ubyte1_e32 v93, v95
	v_cvt_f32_ubyte0_e32 v92, v95
	v_pk_fma_f32 v[94:95], v[0:1], v[104:105], v[106:107] op_sel_hi:[0,1,1]
	v_cvt_f32_ubyte1_e32 v105, v88
	v_cvt_f32_ubyte0_e32 v104, v88
	v_pk_fma_f32 v[12:13], v[0:1], v[104:105], v[12:13] op_sel:[1,0,0]
	v_cvt_f32_ubyte3_e32 v105, v88
	v_cvt_f32_ubyte2_e32 v104, v88
	v_pk_fma_f32 v[14:15], v[0:1], v[104:105], v[14:15] op_sel:[1,0,0]
	v_cvt_f32_ubyte1_e32 v105, v89
	v_cvt_f32_ubyte0_e32 v104, v89
	v_pk_fma_f32 v[24:25], v[0:1], v[104:105], v[24:25] op_sel:[1,0,0]
	v_cvt_f32_ubyte3_e32 v105, v89
	v_cvt_f32_ubyte2_e32 v104, v89
	v_cvt_f32_ubyte1_e32 v89, v90
	v_cvt_f32_ubyte0_e32 v88, v90
	v_pk_fma_f32 v[60:61], v[0:1], v[88:89], v[60:61] op_sel:[1,0,0]
	v_cvt_f32_ubyte3_e32 v89, v90
	v_cvt_f32_ubyte2_e32 v88, v90
	v_pk_fma_f32 v[92:93], v[0:1], v[92:93], v[116:117] op_sel_hi:[0,1,1]
	v_pk_fma_f32 v[62:63], v[0:1], v[88:89], v[62:63] op_sel:[1,0,0]
; DI void phase11b(const Params& P, char* smem_all) {
;     ...
;       for (int k = 0; k < 4; ++k) {
;         acc[2 * k + 0] = __builtin_elementwise_fma(w2, f2{(float)(vw[k] & 0xffu), (float)((vw[k] >> 8) & 0xffu)}, acc[2 * k + 0]);
;         acc[2 * k + 1] = __builtin_elementwise_fma(w2, f2{(float)((vw[k] >> 16) & 0xffu), (float)(vw[k] >> 24)}, acc[2 * k + 1]);
;       }
;     }
;     const float rsum = dpp_row_sum_f(wl);
;     const float wsum = (__int_as_float(__builtin_amdgcn_readlane(__float_as_int(rsum), 0)) + __int_as_float(__builtin_amdgcn_readlane(__float_as_int(rsum), 16)) +
;                         __int_as_float(__builtin_amdgcn_readlane(__float_as_int(rsum), 32)) + __int_as_float(__builtin_amdgcn_readlane(__float_as_int(rsum), 48))) * 0.125f;
; #pragma unroll
;     for (int k = 0; k < 4; ++k) *reinterpret_cast<float4*>(red + g8 * 128 + (lane & 7) * 16 + 4 * k) = make_float4(acc[2 * k][0], acc[2 * k][1], acc[2 * k + 1][0], acc[2 * k + 1][1]);
;     float2 s = make_float2(0.f, 0.f);
; #pragma unroll
;     for (int g = 0; g < 8; ++g) { const float2 a = *reinterpret_cast<const float2*>(red + g * 128 + 2 * lane); s.x += a.x; s.y += a.y; }
;     h2 zo; zo[0] = (_Float16)(s.x - 128.f * wsum); zo[1] = (_Float16)(s.y - 128.f * wsum);
;     *reinterpret_cast<h2*>(Zp + (long)t * 1024 + j * 128 + 2 * lane) = zo;
	v_cvt_f32_ubyte1_e32 v89, v91
	v_cvt_f32_ubyte0_e32 v88, v91
	v_add_f32_e32 v106, v0, v118
	v_pk_fma_f32 v[88:89], v[0:1], v[88:89], v[92:93] op_sel:[1,0,0]
	v_cvt_f32_ubyte3_e32 v93, v91
	v_cvt_f32_ubyte2_e32 v92, v91
	v_pk_fma_f32 v[26:27], v[0:1], v[104:105], v[26:27] op_sel:[1,0,0]
	v_pk_fma_f32 v[90:91], v[0:1], v[92:93], v[94:95] op_sel:[1,0,0]
	v_add_f32_e32 v92, v1, v106
	v_cvt_f32_ubyte1_e32 v1, v80
	v_cvt_f32_ubyte0_e32 v0, v80
	v_pk_fma_f32 v[0:1], v[2:3], v[0:1], v[12:13] op_sel_hi:[0,1,1]
	v_cvt_f32_ubyte3_e32 v13, v80
	v_cvt_f32_ubyte2_e32 v12, v80
	v_pk_fma_f32 v[14:15], v[2:3], v[12:13], v[14:15] op_sel_hi:[0,1,1]
	v_cvt_f32_ubyte1_e32 v13, v81
	v_cvt_f32_ubyte0_e32 v12, v81
	v_pk_fma_f32 v[24:25], v[2:3], v[12:13], v[24:25] op_sel_hi:[0,1,1]
	v_cvt_f32_ubyte3_e32 v13, v81
	v_cvt_f32_ubyte2_e32 v12, v81
	v_pk_fma_f32 v[26:27], v[2:3], v[12:13], v[26:27] op_sel_hi:[0,1,1]
	v_cvt_f32_ubyte1_e32 v13, v82
	v_cvt_f32_ubyte0_e32 v12, v82
	v_pk_fma_f32 v[60:61], v[2:3], v[12:13], v[60:61] op_sel_hi:[0,1,1]
	v_cvt_f32_ubyte3_e32 v13, v82
	v_cvt_f32_ubyte2_e32 v12, v82
	v_pk_fma_f32 v[62:63], v[2:3], v[12:13], v[62:63] op_sel_hi:[0,1,1]
	v_cvt_f32_ubyte1_e32 v13, v83
	v_cvt_f32_ubyte0_e32 v12, v83
	v_pk_fma_f32 v[80:81], v[2:3], v[12:13], v[88:89] op_sel_hi:[0,1,1]
	v_cvt_f32_ubyte3_e32 v13, v83
	v_cvt_f32_ubyte2_e32 v12, v83
	v_pk_fma_f32 v[82:83], v[2:3], v[12:13], v[90:91] op_sel_hi:[0,1,1]
	v_cvt_f32_ubyte1_e32 v13, v72
	v_cvt_f32_ubyte0_e32 v12, v72
	v_pk_fma_f32 v[12:13], v[2:3], v[12:13], v[0:1] op_sel:[1,0,0]
	v_cvt_f32_ubyte3_e32 v1, v72
	v_cvt_f32_ubyte2_e32 v0, v72
	v_pk_fma_f32 v[14:15], v[2:3], v[0:1], v[14:15] op_sel:[1,0,0]
	v_cvt_f32_ubyte1_e32 v1, v73
	v_cvt_f32_ubyte0_e32 v0, v73
	v_pk_fma_f32 v[24:25], v[2:3], v[0:1], v[24:25] op_sel:[1,0,0]
	v_cvt_f32_ubyte3_e32 v1, v73
	v_cvt_f32_ubyte2_e32 v0, v73
	v_pk_fma_f32 v[26:27], v[2:3], v[0:1], v[26:27] op_sel:[1,0,0]
	v_cvt_f32_ubyte1_e32 v1, v74
	v_cvt_f32_ubyte0_e32 v0, v74
	v_pk_fma_f32 v[60:61], v[2:3], v[0:1], v[60:61] op_sel:[1,0,0]
	v_cvt_f32_ubyte3_e32 v1, v74
	v_cvt_f32_ubyte2_e32 v0, v74
	v_pk_fma_f32 v[62:63], v[2:3], v[0:1], v[62:63] op_sel:[1,0,0]
	v_cvt_f32_ubyte1_e32 v1, v75
	v_cvt_f32_ubyte0_e32 v0, v75
	v_add_f32_e32 v88, v2, v92
	v_pk_fma_f32 v[72:73], v[2:3], v[0:1], v[80:81] op_sel:[1,0,0]
	v_cvt_f32_ubyte3_e32 v1, v75
	v_cvt_f32_ubyte2_e32 v0, v75
	v_pk_fma_f32 v[74:75], v[2:3], v[0:1], v[82:83] op_sel:[1,0,0]
	v_add_f32_e32 v0, v3, v88
	ds_write_b128 v213, v[12:15]
	ds_write_b128 v213, v[24:27] offset:16
	ds_write_b128 v213, v[60:63] offset:32
	ds_write_b128 v213, v[72:75] offset:48
	v_add_f32_dpp v0, v0, v0 quad_perm:[1,0,3,2] row_mask:0xf bank_mask:0xf bound_ctrl:1
	ds_read2st64_b64 v[24:27], v224 offset0:4 offset1:5
	v_ashrrev_i32_e32 v169, 31, v168
	v_add_f32_dpp v0, v0, v0 quad_perm:[2,3,0,1] row_mask:0xf bank_mask:0xf bound_ctrl:1
	s_nop 1
	v_add_f32_dpp v0, v0, v0 row_half_mirror row_mask:0xf bank_mask:0xf bound_ctrl:1
	s_nop 1
	v_add_f32_dpp v0, v0, v0 row_mirror row_mask:0xf bank_mask:0xf bound_ctrl:1
	s_nop 0
	v_readlane_b32 s15, v0, 16
	v_readlane_b32 s0, v0, 0
	v_readlane_b32 s1, v0, 32
	v_readlane_b32 s16, v0, 48
	v_mov_b32_e32 v0, s15
	v_add_f32_e32 v0, s0, v0
	v_add_f32_e32 v12, s1, v0
	ds_read2st64_b64 v[0:3], v224 offset1:1
	v_add_f32_e32 v12, s16, v12
	v_mul_f32_e32 v12, 0x3e000000, v12
	v_mul_f32_e32 v60, 0x43000000, v12
	ds_read2st64_b64 v[12:15], v224 offset0:2 offset1:3
	s_waitcnt lgkmcnt(1)
	v_pk_add_f32 v[0:1], v[0:1], 0 op_sel_hi:[1,0]
	s_nop 0
	v_pk_add_f32 v[62:63], v[0:1], v[2:3]
	ds_read2st64_b64 v[0:3], v224 offset0:6 offset1:7
	s_waitcnt lgkmcnt(1)
	v_pk_add_f32 v[12:13], v[62:63], v[12:13]
	s_nop 0
	v_pk_add_f32 v[12:13], v[12:13], v[14:15]
	s_nop 0
	v_pk_add_f32 v[12:13], v[12:13], v[24:25]
	s_nop 0
	v_pk_add_f32 v[12:13], v[12:13], v[26:27]
	s_waitcnt lgkmcnt(0)
	v_pk_add_f32 v[0:1], v[12:13], v[0:1]
	s_nop 0
	v_pk_add_f32 v[0:1], v[0:1], v[2:3]
	s_nop 0
	v_pk_add_f32 v[0:1], v[0:1], v[60:61] op_sel_hi:[1,0] neg_lo:[0,1] neg_hi:[0,1]
	s_nop 0
	v_cvt_pk_f16_f32 v2, v0, v1
	v_lshlrev_b64 v[0:1], 11, v[168:169]
	v_lshl_add_u64 v[0:1], v[220:221], 0, v[0:1]
	global_store_dword v[0:1], v2, off
	s_branch .LBB0_1579
